# P8 a_low loop unrolled over two fragment sets; FFN-up epilogue conv-weight row preloaded before the K loop (both epilogue vmcnt(0) drains removed)
# speedup vs baseline: 1.0330x; 1.0046x over previous
; #define PG8_WAIT_V(n) asm volatile("s_waitcnt vmcnt(" #n ")" ::: "memory")
; #define PG8_BAR __builtin_amdgcn_s_barrier()
; template <class Epi, bool HALO>
; __device__ __forceinline__ void gemm_phase(LAS unsigned char* lds, const Gemm g, const StaticOrder& S, const Epi& E) {
;     ...
;     f32x4 acc[2][2][4][2];
; #pragma unroll
;     for (int a = 0; a < 2; ++a)
; #pragma unroll
;         for (int b = 0; b < 2; ++b)
; #pragma unroll
;             for (int m = 0; m < 4; ++m)
; #pragma unroll
;                 for (int n = 0; n < 2; ++n) acc[a][b][m][n] = (f32x4){0.f, 0.f, 0.f, 0.f};
;     bf16x8 At[4][2], B0[2][2], B1[2][2];
;     const char* cA = A0 + (size_t)cur.pm * tstepA + (size_t)cur.pn * g.a_pn_off * 2; const char* cB = (const char*)g.Bt + (size_t)cur.pn * tstepB;
;     PG8_STAGE(PG8_SB(0, 0), cB, voffB); PG8_STAGE(PG8_SB(0, 1), cB + hstepB, voffB); PG8_STAGE(PG8_SA(0, 0), cA, voffA); PG8_STAGE(PG8_SA(0, 1), cA + hstepA, voffA);
;     if (wr == 1) PG8_BAR;
;     PG8_WAIT_V(2); PG8_BAR;
;     PG8_STAGE(PG8_SB(1, 0), cB + kstepB, voffB); PG8_STAGE(PG8_SA(1, 0), cA + kstep, voffA); PG8_STAGE(PG8_SB(1, 1), cB + hstepB + kstepB, voffB);
;     PG8_WAIT_V(6); PG8_BAR;
;     for (;;) {
;         const bool has_next = S.next(ui + 1, nxt);
;         const char* nA = has_next ? A0 + (size_t)nxt.pm * tstepA + (size_t)nxt.pn * g.a_pn_off * 2 : cA; const char* nB = has_next ? (const char*)g.Bt + (size_t)nxt.pn * tstepB : cB;
;         for (int t = 0; t < nt; t += 2) {
;             const bool last = (t == nt - 2);
;             const char* a1 = cA + (size_t)(t + 1) * kstep;
;             const char* a2 = last ? nA : cA + (size_t)(t + 2) * kstep; const char* b2 = last ? nB : cB + (size_t)(t + 2) * kstepB;
;             const char* a3 = a2 + kstep; const char* b3 = b2 + kstepB;
;             PG8_LDB(B0, 0, 0); PG8_LDB(B1, 0, 1); PG8_SCHED; PG8_LDA(At, 0, 0); PG8_STAGE(PG8_SA(1, 1), a1 + hstepA, voffA);
;     __device__ __forceinline__ void operator()(AccT& acc, const pg8::Unit& u, int wr, int wc, int fr, int fq) const {
;     ...
;         const int wt_t = (4 * wr + wc) * 64 + fq * 16 + fr;
;         f32x4 wreg = (f32x4){0.f, 0.f, 0.f, 0.f};
;         if (wt_t < 256) { const int kind = wt_t >> 6, hf = (wt_t & 63) >> 5, c = ((wt_t & 63) * 4) & 127;
;             wreg = *(const f32x4*)((kind < 3 ? cw + kind * FF2 : cb) + hf * FF + u.pn * 128 + c); }
.LBB0_595:
	s_ashr_i32 s35, s34, 31
	s_lshl_b64 s[12:13], s[34:35], 19
	s_add_u32 s36, s58, s12
	s_addc_u32 s37, s59, s13
	s_and_b64 s[12:13], s[6:7], exec
	s_cselect_b32 s16, s37, s11
	s_cselect_b32 s17, s36, s10
	s_ashr_i32 s31, s30, 31
	s_lshl_b64 s[12:13], s[30:31], 19
	s_add_u32 s38, s54, s12
	s_addc_u32 s39, s55, s13
	s_and_b64 s[12:13], s[6:7], exec
	s_cselect_b32 s31, s39, s9
	s_cselect_b32 s35, s38, s8
	s_add_u32 s41, s8, 0x10000
	s_addc_u32 s42, s9, 0
	s_add_u32 s8, s10, 0x40080
	v_mov_b32_e32 v24, 0
	s_addc_u32 s9, s11, 0
	s_mov_b32 s43, -2
	v_mov_b32_e32 v25, v24
	v_mov_b32_e32 v26, v24
	v_mov_b32_e32 v27, v24
	v_mov_b32_e32 v76, v24
	v_mov_b32_e32 v77, v24
	v_mov_b32_e32 v78, v24
	v_mov_b32_e32 v79, v24
	v_mov_b32_e32 v0, v24
	v_mov_b32_e32 v1, v24
	v_mov_b32_e32 v2, v24
	v_mov_b32_e32 v3, v24
	v_mov_b32_e32 v56, v24
	v_mov_b32_e32 v57, v24
	v_mov_b32_e32 v58, v24
	v_mov_b32_e32 v59, v24
	v_mov_b32_e32 v4, v24
	v_mov_b32_e32 v5, v24
	v_mov_b32_e32 v6, v24
	v_mov_b32_e32 v7, v24
	v_mov_b32_e32 v60, v24
	v_mov_b32_e32 v61, v24
	v_mov_b32_e32 v62, v24
	v_mov_b32_e32 v63, v24
	v_mov_b32_e32 v16, v24
	v_mov_b32_e32 v17, v24
	v_mov_b32_e32 v18, v24
	v_mov_b32_e32 v19, v24
	v_mov_b32_e32 v80, v24
	v_mov_b32_e32 v81, v24
	v_mov_b32_e32 v82, v24
	v_mov_b32_e32 v83, v24
	v_mov_b32_e32 v28, v24
	v_mov_b32_e32 v29, v24
	v_mov_b32_e32 v30, v24
	v_mov_b32_e32 v31, v24
	v_mov_b32_e32 v88, v24
	v_mov_b32_e32 v89, v24
	v_mov_b32_e32 v90, v24
	v_mov_b32_e32 v91, v24
	v_mov_b32_e32 v8, v24
	v_mov_b32_e32 v9, v24
	v_mov_b32_e32 v10, v24
	v_mov_b32_e32 v11, v24
	v_mov_b32_e32 v64, v24
	v_mov_b32_e32 v65, v24
	v_mov_b32_e32 v66, v24
	v_mov_b32_e32 v67, v24
	v_mov_b32_e32 v12, v24
	v_mov_b32_e32 v13, v24
	v_mov_b32_e32 v14, v24
	v_mov_b32_e32 v15, v24
	v_mov_b32_e32 v68, v24
	v_mov_b32_e32 v69, v24
	v_mov_b32_e32 v70, v24
	v_mov_b32_e32 v71, v24
	v_mov_b32_e32 v20, v24
	v_mov_b32_e32 v21, v24
	v_mov_b32_e32 v22, v24
	v_mov_b32_e32 v23, v24
	v_mov_b32_e32 v84, v24
	v_mov_b32_e32 v85, v24
	v_mov_b32_e32 v86, v24
	v_mov_b32_e32 v87, v24
	v_mov_b32_e32 v48, v24
	v_mov_b32_e32 v49, v24
	v_mov_b32_e32 v50, v24
	v_mov_b32_e32 v51, v24
	v_mov_b32_e32 v92, v24
	v_mov_b32_e32 v93, v24
	v_mov_b32_e32 v94, v24
	v_mov_b32_e32 v95, v24
	v_mov_b32_e32 v32, v24
	v_mov_b32_e32 v33, v24
	v_mov_b32_e32 v34, v24
	v_mov_b32_e32 v35, v24
	v_mov_b32_e32 v112, v24
	v_mov_b32_e32 v113, v24
	v_mov_b32_e32 v114, v24
	v_mov_b32_e32 v115, v24
	v_mov_b32_e32 v36, v24
	v_mov_b32_e32 v37, v24
	v_mov_b32_e32 v38, v24
	v_mov_b32_e32 v39, v24
	v_mov_b32_e32 v124, v24
	v_mov_b32_e32 v125, v24
	v_mov_b32_e32 v126, v24
	v_mov_b32_e32 v127, v24
	v_mov_b32_e32 v72, v24
	v_mov_b32_e32 v73, v24
	v_mov_b32_e32 v74, v24
	v_mov_b32_e32 v75, v24
	v_mov_b32_e32 v96, v24
	v_mov_b32_e32 v97, v24
	v_mov_b32_e32 v98, v24
	v_mov_b32_e32 v99, v24
	v_mov_b32_e32 v52, v24
	v_mov_b32_e32 v53, v24
	v_mov_b32_e32 v54, v24
	v_mov_b32_e32 v55, v24
	v_mov_b32_e32 v108, v24
	v_mov_b32_e32 v109, v24
	v_mov_b32_e32 v110, v24
	v_mov_b32_e32 v111, v24
	v_mov_b32_e32 v40, v24
	v_mov_b32_e32 v41, v24
	v_mov_b32_e32 v42, v24
	v_mov_b32_e32 v43, v24
	v_mov_b32_e32 v128, v24
	v_mov_b32_e32 v129, v24
	v_mov_b32_e32 v130, v24
	v_mov_b32_e32 v131, v24
	v_mov_b32_e32 v44, v24
	v_mov_b32_e32 v45, v24
	v_mov_b32_e32 v46, v24
	v_mov_b32_e32 v47, v24
	v_mov_b32_e32 v140, v24
	v_mov_b32_e32 v141, v24
	v_mov_b32_e32 v142, v24
	v_mov_b32_e32 v143, v24
	v_mov_b32_e32 v100, v24
	v_mov_b32_e32 v101, v24
	v_mov_b32_e32 v102, v24
	v_mov_b32_e32 v103, v24
	v_mov_b32_e32 v104, v24
	v_mov_b32_e32 v105, v24
	v_mov_b32_e32 v106, v24
	v_mov_b32_e32 v107, v24
	v_readfirstlane_b32 s95, v220
	s_lshr_b32 s95, s95, 6
	s_cmp_gt_u32 s95, 3
	s_cbranch_scc1 .Lwp5_skip
	s_mul_i32 s96, s95, 0x5800
	s_add_u32 s96, s72, s96
	s_addc_u32 s97, s73, 0
	s_cmp_lt_u32 s95, 3
	s_cselect_b32 s96, s96, s74
	s_cselect_b32 s97, s97, s75
	s_lshl_b32 s95, s40, 9
	s_add_u32 s96, s96, s95
	s_addc_u32 s97, s97, 0
	v_and_b32_e32 v244, 63, v220
	v_lshrrev_b32_e32 v245, 5, v244
	v_mul_u32_u24_e32 v245, 0x2c00, v245
	v_and_b32_e32 v244, 31, v244
	v_lshl_add_u32 v244, v244, 4, v245
	global_load_dwordx4 v[248:251], v244, s[96:97]
.Lwp5_skip:
.LBB0_596:
	ds_read_b128 v[116:119], v222
	ds_read_b128 v[120:123], v222 offset:1024
	ds_read_b128 v[132:135], v222 offset:2048
	ds_read_b128 v[136:139], v222 offset:3072
	ds_read_b128 v[144:147], v223
	ds_read_b128 v[148:151], v223 offset:1024
	ds_read_b128 v[152:155], v223 offset:2048
	ds_read_b128 v[156:159], v223 offset:3072
	s_add_u32 s10, s8, 0xfffc0080
	s_addc_u32 s11, s9, -1
	s_cmp_eq_u32 s43, 12
	s_cselect_b32 s13, s16, s11
	s_cselect_b32 s12, s17, s10
	s_cselect_b32 s11, s31, s42
	s_cselect_b32 s10, s35, s41
	v_lshl_add_u64 v[210:211], s[8:9], 0, v[186:187]
	s_add_i32 m0, s60, 0xc000
	ds_read_b128 v[160:163], v224
	ds_read_b128 v[164:167], v224 offset:1024
	ds_read_b128 v[168:171], v224 offset:2048
	ds_read_b128 v[172:175], v224 offset:3072
	ds_read_b128 v[194:197], v224 offset:4096
	ds_read_b128 v[198:201], v224 offset:5120
	ds_read_b128 v[202:205], v224 offset:6144
	ds_read_b128 v[206:209], v224 offset:7168
	global_load_lds_dwordx4 v[210:211], off
	v_lshl_add_u64 v[210:211], s[8:9], 0, v[188:189]
	s_add_i32 m0, s60, 0xe000
	s_nop 0
	global_load_lds_dwordx4 v[210:211], off
	s_waitcnt vmcnt(8)
	s_waitcnt lgkmcnt(0)
	s_barrier
; #define PG8_STAGE(bufoff, gbase, voff) do { _Pragma("unroll") for (int _i = 0; _i < 2; ++_i) \
;         __builtin_amdgcn_global_load_lds((const unsigned*)((const char*)(gbase) + (voff)[_i]), (LAS unsigned*)(lds + (bufoff) + ldsw + _i * 8192), 16, 0, 0); } while (0)
; #define PG8_LDA(dst, b, h) do { _Pragma("unroll") for (int m = 0; m < 4; ++m) _Pragma("unroll") for (int k = 0; k < 2; ++k) dst[m][k] = *(const LAS bf16x8*)(lds + PG8_SA(b, h) + aoff + m * 2048 + k * 1024); } while (0)
; #define PG8_MMA(ai, bj, At, Bt) do { __builtin_amdgcn_s_setprio(1); _Pragma("unroll") for (int m = 0; m < 4; ++m) _Pragma("unroll") for (int n = 0; n < 2; ++n) _Pragma("unroll") for (int k = 0; k < 2; ++k) \
;         acc[ai][bj][m][n] = __builtin_amdgcn_mfma_f32_16x16x32_bf16(Bt[n][k], At[m][k], acc[ai][bj][m][n], 0, 0, 0); __builtin_amdgcn_s_setprio(0); } while (0)
; #define PG8_WAIT_V(n) asm volatile("s_waitcnt vmcnt(" #n ")" ::: "memory")
; #define PG8_WAIT_L(n) asm volatile("s_waitcnt lgkmcnt(" #n ")" ::: "memory")
; #define PG8_BAR __builtin_amdgcn_s_barrier()
; #define PG8_SCHED __builtin_amdgcn_sched_barrier(0)
; template <class Epi, bool HALO>
; __device__ __forceinline__ void gemm_phase(LAS unsigned char* lds, const Gemm g, const StaticOrder& S, const Epi& E) {
;     ...
;             PG8_WAIT_V(8); PG8_WAIT_L(0); PG8_BAR; PG8_MMA(0, 0, At, B0); PG8_MMA(0, 1, At, B1); PG8_BAR; PG8_SCHED;
;             PG8_LDA(At, 0, 1); PG8_STAGE(PG8_SB(0, 0), b2, voffB); PG8_STAGE(PG8_SB(0, 1), b2 + hstepB, voffB); PG8_STAGE(PG8_SA(0, 0), a2, voffA);
;             PG8_WAIT_V(8); PG8_WAIT_L(0); PG8_BAR; PG8_MMA(1, 0, At, B0); PG8_MMA(1, 1, At, B1); PG8_BAR; PG8_SCHED;
	s_setprio 1
	s_waitcnt lgkmcnt(0)
	v_mfma_f32_16x16x32_bf16 v[104:107], v[116:119], v[160:163], v[104:107]
	v_mfma_f32_16x16x32_bf16 v[100:103], v[132:135], v[160:163], v[100:103]
	v_mfma_f32_16x16x32_bf16 v[140:143], v[116:119], v[168:171], v[140:143]
	v_mfma_f32_16x16x32_bf16 v[44:47], v[132:135], v[168:171], v[44:47]
	v_mfma_f32_16x16x32_bf16 v[128:131], v[116:119], v[194:197], v[128:131]
	v_mfma_f32_16x16x32_bf16 v[40:43], v[132:135], v[194:197], v[40:43]
	v_mfma_f32_16x16x32_bf16 v[108:111], v[116:119], v[202:205], v[108:111]
	v_mfma_f32_16x16x32_bf16 v[52:55], v[132:135], v[202:205], v[52:55]
	v_mfma_f32_16x16x32_bf16 v[104:107], v[120:123], v[164:167], v[104:107]
	v_mfma_f32_16x16x32_bf16 v[100:103], v[136:139], v[164:167], v[100:103]
	v_mfma_f32_16x16x32_bf16 v[140:143], v[120:123], v[172:175], v[140:143]
	v_mfma_f32_16x16x32_bf16 v[44:47], v[136:139], v[172:175], v[44:47]
	v_mfma_f32_16x16x32_bf16 v[128:131], v[120:123], v[198:201], v[128:131]
	v_mfma_f32_16x16x32_bf16 v[40:43], v[136:139], v[198:201], v[40:43]
	v_mfma_f32_16x16x32_bf16 v[108:111], v[120:123], v[206:209], v[108:111]
	v_mfma_f32_16x16x32_bf16 v[52:55], v[136:139], v[206:209], v[52:55]
	s_setprio 0
	s_setprio 1
	v_mfma_f32_16x16x32_bf16 v[96:99], v[144:147], v[160:163], v[96:99]
	v_mfma_f32_16x16x32_bf16 v[72:75], v[152:155], v[160:163], v[72:75]
	v_mfma_f32_16x16x32_bf16 v[124:127], v[144:147], v[168:171], v[124:127]
	v_mfma_f32_16x16x32_bf16 v[36:39], v[152:155], v[168:171], v[36:39]
	v_mfma_f32_16x16x32_bf16 v[112:115], v[144:147], v[194:197], v[112:115]
	v_mfma_f32_16x16x32_bf16 v[32:35], v[152:155], v[194:197], v[32:35]
	v_mfma_f32_16x16x32_bf16 v[92:95], v[144:147], v[202:205], v[92:95]
	v_mfma_f32_16x16x32_bf16 v[48:51], v[152:155], v[202:205], v[48:51]
	v_mfma_f32_16x16x32_bf16 v[96:99], v[148:151], v[164:167], v[96:99]
	v_mfma_f32_16x16x32_bf16 v[72:75], v[156:159], v[164:167], v[72:75]
	v_mfma_f32_16x16x32_bf16 v[124:127], v[148:151], v[172:175], v[124:127]
	v_mfma_f32_16x16x32_bf16 v[36:39], v[156:159], v[172:175], v[36:39]
	v_mfma_f32_16x16x32_bf16 v[112:115], v[148:151], v[198:201], v[112:115]
	v_mfma_f32_16x16x32_bf16 v[32:35], v[156:159], v[198:201], v[32:35]
	v_mfma_f32_16x16x32_bf16 v[92:95], v[148:151], v[206:209], v[92:95]
	v_mfma_f32_16x16x32_bf16 v[48:51], v[156:159], v[206:209], v[48:51]
	s_setprio 0
	s_barrier
	s_add_i32 s50, s76, s57
	v_lshl_add_u64 v[210:211], s[10:11], 0, v[176:177]
	s_mov_b32 m0, s50
	ds_read_b128 v[160:163], v224 offset:16384
	ds_read_b128 v[164:167], v224 offset:17408
	ds_read_b128 v[168:171], v224 offset:18432
	ds_read_b128 v[172:175], v224 offset:19456
	ds_read_b128 v[194:197], v224 offset:20480
	ds_read_b128 v[198:201], v224 offset:21504
	ds_read_b128 v[202:205], v224 offset:22528
	ds_read_b128 v[206:209], v224 offset:23552
	global_load_lds_dwordx4 v[210:211], off
	s_add_i32 m0, s50, 0x2000
	s_add_u32 s50, s10, 0x4000
	v_lshl_add_u64 v[210:211], s[10:11], 0, v[180:181]
	s_addc_u32 s51, s11, 0
	s_add_i32 s93, s77, s57
	global_load_lds_dwordx4 v[210:211], off
	v_lshl_add_u64 v[210:211], s[50:51], 0, v[176:177]
	s_mov_b32 m0, s93
	v_lshl_add_u64 v[212:213], s[12:13], 0, v[182:183]
	global_load_lds_dwordx4 v[210:211], off
	v_lshl_add_u64 v[210:211], s[50:51], 0, v[180:181]
	s_add_i32 m0, s93, 0x2000
	s_nop 0
	global_load_lds_dwordx4 v[210:211], off
	v_lshl_add_u64 v[210:211], s[12:13], 0, v[178:179]
	s_mov_b32 m0, s60
	s_nop 0
	global_load_lds_dwordx4 v[210:211], off
	s_mov_b32 m0, s61
	s_nop 0
	global_load_lds_dwordx4 v[212:213], off
	s_waitcnt vmcnt(8)
	s_waitcnt lgkmcnt(0)
	s_barrier
	s_setprio 1
	s_waitcnt lgkmcnt(0)
	v_mfma_f32_16x16x32_bf16 v[84:87], v[116:119], v[160:163], v[84:87]
	v_mfma_f32_16x16x32_bf16 v[20:23], v[132:135], v[160:163], v[20:23]
	v_mfma_f32_16x16x32_bf16 v[68:71], v[116:119], v[168:171], v[68:71]
	v_mfma_f32_16x16x32_bf16 v[12:15], v[132:135], v[168:171], v[12:15]
	v_mfma_f32_16x16x32_bf16 v[64:67], v[116:119], v[194:197], v[64:67]
	v_mfma_f32_16x16x32_bf16 v[8:11], v[132:135], v[194:197], v[8:11]
	v_mfma_f32_16x16x32_bf16 v[88:91], v[116:119], v[202:205], v[88:91]
	v_mfma_f32_16x16x32_bf16 v[28:31], v[132:135], v[202:205], v[28:31]
	v_mfma_f32_16x16x32_bf16 v[84:87], v[120:123], v[164:167], v[84:87]
	v_mfma_f32_16x16x32_bf16 v[20:23], v[136:139], v[164:167], v[20:23]
	v_mfma_f32_16x16x32_bf16 v[68:71], v[120:123], v[172:175], v[68:71]
	v_mfma_f32_16x16x32_bf16 v[12:15], v[136:139], v[172:175], v[12:15]
	v_mfma_f32_16x16x32_bf16 v[64:67], v[120:123], v[198:201], v[64:67]
	v_mfma_f32_16x16x32_bf16 v[8:11], v[136:139], v[198:201], v[8:11]
	v_mfma_f32_16x16x32_bf16 v[88:91], v[120:123], v[206:209], v[88:91]
	v_mfma_f32_16x16x32_bf16 v[28:31], v[136:139], v[206:209], v[28:31]
	s_setprio 0
	s_setprio 1
	v_mfma_f32_16x16x32_bf16 v[80:83], v[144:147], v[160:163], v[80:83]
	v_mfma_f32_16x16x32_bf16 v[16:19], v[152:155], v[160:163], v[16:19]
	v_mfma_f32_16x16x32_bf16 v[60:63], v[144:147], v[168:171], v[60:63]
	v_mfma_f32_16x16x32_bf16 v[4:7], v[152:155], v[168:171], v[4:7]
	v_mfma_f32_16x16x32_bf16 v[56:59], v[144:147], v[194:197], v[56:59]
	v_mfma_f32_16x16x32_bf16 v[0:3], v[152:155], v[194:197], v[0:3]
	v_mfma_f32_16x16x32_bf16 v[76:79], v[144:147], v[202:205], v[76:79]
	v_mfma_f32_16x16x32_bf16 v[24:27], v[152:155], v[202:205], v[24:27]
	v_mfma_f32_16x16x32_bf16 v[80:83], v[148:151], v[164:167], v[80:83]
	v_mfma_f32_16x16x32_bf16 v[16:19], v[156:159], v[164:167], v[16:19]
	v_mfma_f32_16x16x32_bf16 v[60:63], v[148:151], v[172:175], v[60:63]
	v_mfma_f32_16x16x32_bf16 v[4:7], v[156:159], v[172:175], v[4:7]
	v_mfma_f32_16x16x32_bf16 v[56:59], v[148:151], v[198:201], v[56:59]
	v_mfma_f32_16x16x32_bf16 v[0:3], v[156:159], v[198:201], v[0:3]
	v_mfma_f32_16x16x32_bf16 v[76:79], v[148:151], v[206:209], v[76:79]
	v_mfma_f32_16x16x32_bf16 v[24:27], v[156:159], v[206:209], v[24:27]
	s_setprio 0
	s_barrier
; #define PG8_STAGE(bufoff, gbase, voff) do { _Pragma("unroll") for (int _i = 0; _i < 2; ++_i) \
;         __builtin_amdgcn_global_load_lds((const unsigned*)((const char*)(gbase) + (voff)[_i]), (LAS unsigned*)(lds + (bufoff) + ldsw + _i * 8192), 16, 0, 0); } while (0)
; #define PG8_LDA(dst, b, h) do { _Pragma("unroll") for (int m = 0; m < 4; ++m) _Pragma("unroll") for (int k = 0; k < 2; ++k) dst[m][k] = *(const LAS bf16x8*)(lds + PG8_SA(b, h) + aoff + m * 2048 + k * 1024); } while (0)
; #define PG8_LDB(dst, b, h) do { _Pragma("unroll") for (int n = 0; n < 2; ++n) _Pragma("unroll") for (int k = 0; k < 2; ++k) dst[n][k] = *(const LAS bf16x8*)(lds + PG8_SB(b, h) + boff + n * 2048 + k * 1024); } while (0)
; #define PG8_MMA(ai, bj, At, Bt) do { __builtin_amdgcn_s_setprio(1); _Pragma("unroll") for (int m = 0; m < 4; ++m) _Pragma("unroll") for (int n = 0; n < 2; ++n) _Pragma("unroll") for (int k = 0; k < 2; ++k) \
;         acc[ai][bj][m][n] = __builtin_amdgcn_mfma_f32_16x16x32_bf16(Bt[n][k], At[m][k], acc[ai][bj][m][n], 0, 0, 0); __builtin_amdgcn_s_setprio(0); } while (0)
; #define PG8_WAIT_V(n) asm volatile("s_waitcnt vmcnt(" #n ")" ::: "memory")
; #define PG8_WAIT_L(n) asm volatile("s_waitcnt lgkmcnt(" #n ")" ::: "memory")
; #define PG8_BAR __builtin_amdgcn_s_barrier()
; #define PG8_SCHED __builtin_amdgcn_sched_barrier(0)
; template <class Epi, bool HALO>
; __device__ __forceinline__ void gemm_phase(LAS unsigned char* lds, const Gemm g, const StaticOrder& S, const Epi& E) {
;     ...
;             PG8_LDB(B0, 1, 0); PG8_LDB(B1, 1, 1); PG8_SCHED; PG8_LDA(At, 1, 0); PG8_STAGE(PG8_SA(0, 1), a2 + hstepA, voffA);
;             PG8_WAIT_V(8); PG8_WAIT_L(0); PG8_BAR; PG8_MMA(0, 0, At, B0); PG8_MMA(0, 1, At, B1); PG8_BAR; PG8_SCHED;
;             PG8_LDA(At, 1, 1); PG8_STAGE(PG8_SB(1, 0), b3, voffB); PG8_STAGE(PG8_SB(1, 1), b3 + hstepB, voffB); PG8_STAGE(PG8_SA(1, 0), a3, voffA);
	s_add_i32 s50, 0, 0x18000
	s_add_i32 s51, 0, 0x1c000
	v_add_u32_e32 v136, s50, v221
	v_add_u32_e32 v156, s51, v221
	ds_read_b128 v[116:119], v136
	ds_read_b128 v[120:123], v136 offset:1024
	ds_read_b128 v[132:135], v136 offset:2048
	ds_read_b128 v[136:139], v136 offset:3072
	ds_read_b128 v[144:147], v156
	ds_read_b128 v[148:151], v156 offset:1024
	ds_read_b128 v[152:155], v156 offset:2048
	ds_read_b128 v[156:159], v156 offset:3072
	s_add_u32 s12, s12, 0x40000
	s_addc_u32 s13, s13, 0
	s_mov_b32 m0, s62
	v_lshl_add_u64 v[214:215], s[12:13], 0, v[178:179]
	ds_read_b128 v[160:163], v224 offset:32768
	ds_read_b128 v[164:167], v224 offset:33792
	ds_read_b128 v[168:171], v224 offset:34816
	ds_read_b128 v[172:175], v224 offset:35840
	ds_read_b128 v[194:197], v224 offset:36864
	ds_read_b128 v[198:201], v224 offset:37888
	ds_read_b128 v[202:205], v224 offset:38912
	ds_read_b128 v[206:209], v224 offset:39936
	global_load_lds_dwordx4 v[214:215], off
	v_lshl_add_u64 v[214:215], s[12:13], 0, v[182:183]
	s_mov_b32 m0, s63
	s_nop 0
	global_load_lds_dwordx4 v[214:215], off
	s_waitcnt vmcnt(8)
	s_waitcnt lgkmcnt(0)
	s_barrier
	s_setprio 1
	s_waitcnt lgkmcnt(0)
	v_mfma_f32_16x16x32_bf16 v[104:107], v[116:119], v[160:163], v[104:107]
	v_mfma_f32_16x16x32_bf16 v[100:103], v[132:135], v[160:163], v[100:103]
	v_mfma_f32_16x16x32_bf16 v[140:143], v[116:119], v[168:171], v[140:143]
	v_mfma_f32_16x16x32_bf16 v[44:47], v[132:135], v[168:171], v[44:47]
	v_mfma_f32_16x16x32_bf16 v[128:131], v[116:119], v[194:197], v[128:131]
	v_mfma_f32_16x16x32_bf16 v[40:43], v[132:135], v[194:197], v[40:43]
	v_mfma_f32_16x16x32_bf16 v[108:111], v[116:119], v[202:205], v[108:111]
	v_mfma_f32_16x16x32_bf16 v[52:55], v[132:135], v[202:205], v[52:55]
	v_mfma_f32_16x16x32_bf16 v[104:107], v[120:123], v[164:167], v[104:107]
	v_mfma_f32_16x16x32_bf16 v[100:103], v[136:139], v[164:167], v[100:103]
	v_mfma_f32_16x16x32_bf16 v[140:143], v[120:123], v[172:175], v[140:143]
	v_mfma_f32_16x16x32_bf16 v[44:47], v[136:139], v[172:175], v[44:47]
	v_mfma_f32_16x16x32_bf16 v[128:131], v[120:123], v[198:201], v[128:131]
	v_mfma_f32_16x16x32_bf16 v[40:43], v[136:139], v[198:201], v[40:43]
	v_mfma_f32_16x16x32_bf16 v[108:111], v[120:123], v[206:209], v[108:111]
	v_mfma_f32_16x16x32_bf16 v[52:55], v[136:139], v[206:209], v[52:55]
	s_setprio 0
	s_setprio 1
	v_mfma_f32_16x16x32_bf16 v[96:99], v[144:147], v[160:163], v[96:99]
	v_mfma_f32_16x16x32_bf16 v[72:75], v[152:155], v[160:163], v[72:75]
	v_mfma_f32_16x16x32_bf16 v[124:127], v[144:147], v[168:171], v[124:127]
	v_mfma_f32_16x16x32_bf16 v[36:39], v[152:155], v[168:171], v[36:39]
	v_mfma_f32_16x16x32_bf16 v[112:115], v[144:147], v[194:197], v[112:115]
	v_mfma_f32_16x16x32_bf16 v[32:35], v[152:155], v[194:197], v[32:35]
	v_mfma_f32_16x16x32_bf16 v[92:95], v[144:147], v[202:205], v[92:95]
	v_mfma_f32_16x16x32_bf16 v[48:51], v[152:155], v[202:205], v[48:51]
	v_mfma_f32_16x16x32_bf16 v[96:99], v[148:151], v[164:167], v[96:99]
	v_mfma_f32_16x16x32_bf16 v[72:75], v[156:159], v[164:167], v[72:75]
	v_mfma_f32_16x16x32_bf16 v[124:127], v[148:151], v[172:175], v[124:127]
	v_mfma_f32_16x16x32_bf16 v[36:39], v[156:159], v[172:175], v[36:39]
	v_mfma_f32_16x16x32_bf16 v[112:115], v[148:151], v[198:201], v[112:115]
	v_mfma_f32_16x16x32_bf16 v[32:35], v[156:159], v[198:201], v[32:35]
	v_mfma_f32_16x16x32_bf16 v[92:95], v[148:151], v[206:209], v[92:95]
	v_mfma_f32_16x16x32_bf16 v[48:51], v[156:159], v[206:209], v[48:51]
	s_setprio 0
	s_barrier
	s_add_u32 s12, s10, 0x8000
	s_addc_u32 s13, s11, 0
	s_add_i32 s50, s50, s57
	v_lshl_add_u64 v[214:215], s[12:13], 0, v[176:177]
	s_mov_b32 m0, s50
	ds_read_b128 v[160:163], v224 offset:49152
	ds_read_b128 v[164:167], v224 offset:50176
	ds_read_b128 v[168:171], v224 offset:51200
	ds_read_b128 v[172:175], v224 offset:52224
	ds_read_b128 v[194:197], v224 offset:53248
	ds_read_b128 v[198:201], v224 offset:54272
	ds_read_b128 v[202:205], v224 offset:55296
	ds_read_b128 v[206:209], v224 offset:56320
	global_load_lds_dwordx4 v[214:215], off
	s_add_i32 m0, s50, 0x2000
	s_add_u32 s10, s10, 0xc000
	v_lshl_add_u64 v[214:215], s[12:13], 0, v[180:181]
	s_addc_u32 s11, s11, 0
	s_add_i32 s12, s51, s57
	global_load_lds_dwordx4 v[214:215], off
	v_lshl_add_u64 v[214:215], s[10:11], 0, v[176:177]
	s_mov_b32 m0, s12
	v_lshl_add_u64 v[210:211], v[210:211], 0, s[26:27]
	global_load_lds_dwordx4 v[214:215], off
	v_lshl_add_u64 v[214:215], s[10:11], 0, v[180:181]
	s_add_i32 m0, s12, 0x2000
	s_nop 0
	global_load_lds_dwordx4 v[214:215], off
	s_mov_b32 m0, s68
	s_nop 0
	global_load_lds_dwordx4 v[210:211], off
	v_lshl_add_u64 v[210:211], v[212:213], 0, s[26:27]
	s_mov_b32 m0, s69
	s_nop 0
	global_load_lds_dwordx4 v[210:211], off
	s_waitcnt vmcnt(8)
	s_waitcnt lgkmcnt(0)
	s_barrier
; #define PG8_MMA(ai, bj, At, Bt) do { __builtin_amdgcn_s_setprio(1); _Pragma("unroll") for (int m = 0; m < 4; ++m) _Pragma("unroll") for (int n = 0; n < 2; ++n) _Pragma("unroll") for (int k = 0; k < 2; ++k) \
;         acc[ai][bj][m][n] = __builtin_amdgcn_mfma_f32_16x16x32_bf16(Bt[n][k], At[m][k], acc[ai][bj][m][n], 0, 0, 0); __builtin_amdgcn_s_setprio(0); } while (0)
; #define PG8_WAIT_V(n) asm volatile("s_waitcnt vmcnt(" #n ")" ::: "memory")
; #define PG8_WAIT_L(n) asm volatile("s_waitcnt lgkmcnt(" #n ")" ::: "memory")
; #define PG8_BAR __builtin_amdgcn_s_barrier()
; #define PG8_SCHED __builtin_amdgcn_sched_barrier(0)
; template <class Epi, bool HALO>
; __device__ __forceinline__ void gemm_phase(LAS unsigned char* lds, const Gemm g, const StaticOrder& S, const Epi& E) {
;     ...
;             PG8_WAIT_V(8); PG8_WAIT_L(0); PG8_BAR; PG8_MMA(1, 0, At, B0); PG8_MMA(1, 1, At, B1); PG8_BAR; PG8_SCHED;
;         }
;         if (wr == 0) PG8_BAR;
;     __device__ __forceinline__ void operator()(AccT& acc, const pg8::Unit& u, int wr, int wc, int fr, int fq) const {
;     ...
;         const int wt_t = (4 * wr + wc) * 64 + fq * 16 + fr;
;         f32x4 wreg = (f32x4){0.f, 0.f, 0.f, 0.f};
;         if (wt_t < 256) { const int kind = wt_t >> 6, hf = (wt_t & 63) >> 5, c = ((wt_t & 63) * 4) & 127;
;             wreg = *(const f32x4*)((kind < 3 ? cw + kind * FF2 : cb) + hf * FF + u.pn * 128 + c); }
	s_setprio 1
	s_waitcnt lgkmcnt(0)
	v_mfma_f32_16x16x32_bf16 v[84:87], v[116:119], v[160:163], v[84:87]
	v_mfma_f32_16x16x32_bf16 v[20:23], v[132:135], v[160:163], v[20:23]
	v_mfma_f32_16x16x32_bf16 v[68:71], v[116:119], v[168:171], v[68:71]
	v_mfma_f32_16x16x32_bf16 v[12:15], v[132:135], v[168:171], v[12:15]
	v_mfma_f32_16x16x32_bf16 v[64:67], v[116:119], v[194:197], v[64:67]
	v_mfma_f32_16x16x32_bf16 v[8:11], v[132:135], v[194:197], v[8:11]
	v_mfma_f32_16x16x32_bf16 v[88:91], v[116:119], v[202:205], v[88:91]
	v_mfma_f32_16x16x32_bf16 v[28:31], v[132:135], v[202:205], v[28:31]
	v_mfma_f32_16x16x32_bf16 v[84:87], v[120:123], v[164:167], v[84:87]
	v_mfma_f32_16x16x32_bf16 v[20:23], v[136:139], v[164:167], v[20:23]
	v_mfma_f32_16x16x32_bf16 v[68:71], v[120:123], v[172:175], v[68:71]
	v_mfma_f32_16x16x32_bf16 v[12:15], v[136:139], v[172:175], v[12:15]
	v_mfma_f32_16x16x32_bf16 v[64:67], v[120:123], v[198:201], v[64:67]
	v_mfma_f32_16x16x32_bf16 v[8:11], v[136:139], v[198:201], v[8:11]
	v_mfma_f32_16x16x32_bf16 v[88:91], v[120:123], v[206:209], v[88:91]
	v_mfma_f32_16x16x32_bf16 v[28:31], v[136:139], v[206:209], v[28:31]
	s_setprio 0
	s_setprio 1
	v_mfma_f32_16x16x32_bf16 v[80:83], v[144:147], v[160:163], v[80:83]
	v_mfma_f32_16x16x32_bf16 v[16:19], v[152:155], v[160:163], v[16:19]
	v_mfma_f32_16x16x32_bf16 v[60:63], v[144:147], v[168:171], v[60:63]
	v_mfma_f32_16x16x32_bf16 v[4:7], v[152:155], v[168:171], v[4:7]
	v_mfma_f32_16x16x32_bf16 v[56:59], v[144:147], v[194:197], v[56:59]
	v_mfma_f32_16x16x32_bf16 v[0:3], v[152:155], v[194:197], v[0:3]
	v_mfma_f32_16x16x32_bf16 v[76:79], v[144:147], v[202:205], v[76:79]
	v_mfma_f32_16x16x32_bf16 v[24:27], v[152:155], v[202:205], v[24:27]
	v_mfma_f32_16x16x32_bf16 v[80:83], v[148:151], v[164:167], v[80:83]
	v_mfma_f32_16x16x32_bf16 v[16:19], v[156:159], v[164:167], v[16:19]
	v_mfma_f32_16x16x32_bf16 v[60:63], v[148:151], v[172:175], v[60:63]
	v_mfma_f32_16x16x32_bf16 v[4:7], v[156:159], v[172:175], v[4:7]
	v_mfma_f32_16x16x32_bf16 v[56:59], v[148:151], v[198:201], v[56:59]
	v_mfma_f32_16x16x32_bf16 v[0:3], v[156:159], v[198:201], v[0:3]
	v_mfma_f32_16x16x32_bf16 v[76:79], v[148:151], v[206:209], v[76:79]
	v_mfma_f32_16x16x32_bf16 v[24:27], v[156:159], v[206:209], v[24:27]
	s_setprio 0
	s_barrier
	s_add_i32 s43, s43, 2
	s_add_u32 s41, s41, 0x10000
	s_addc_u32 s42, s42, 0
	s_add_u32 s8, s8, 0x100
	s_addc_u32 s9, s9, 0
	s_cmp_gt_u32 s43, 13
	s_cbranch_scc0 .LBB0_596
	s_and_b64 vcc, exec, s[28:29]
	s_cbranch_vccz .LBB0_599
	s_barrier
.LBB0_599:
	s_mov_b32 s31, s56
	v_mov_b32_e32 v116, v220
	s_mov_b32 s35, s67
	s_lshl_b32 s16, s31, 8
	v_bfe_u32 v120, v116, 4, 2
	s_lshl_b32 s11, s35, 6
	v_and_b32_e32 v198, 15, v116
	s_add_i32 s11, s11, s16
	v_lshlrev_b32_e32 v199, 4, v120
	v_or3_b32 v122, s11, v198, v199
	s_lshl_b32 s10, s40, 7
	v_cmp_gt_i32_e64 s[8:9], s70, v122
	v_mov_b32_e32 v116, 0
	v_mov_b32_e32 v117, 0
	v_mov_b32_e32 v118, 0
	v_mov_b32_e32 v119, 0
	s_and_saveexec_b64 s[12:13], s[8:9]
	s_cbranch_execz .LBB0_601
	s_ashr_i32 s11, s11, 6
	s_mul_i32 s42, s11, 0x1600
	s_ashr_i32 s43, s42, 31
	s_lshl_b64 s[42:43], s[42:43], 2
	s_add_u32 s17, s72, s42
	v_bfe_u32 v116, v122, 5, 1
	s_addc_u32 s41, s73, s43
	s_cmp_lt_i32 s11, 3
	v_mul_u32_u24_e32 v116, 0xb00, v116
	s_cselect_b32 s43, s41, s75
	s_cselect_b32 s42, s17, s74
	v_lshlrev_b32_e32 v184, 2, v116
	v_lshl_add_u64 v[116:117], s[42:43], 0, v[184:185]
	s_ashr_i32 s11, s10, 31
	v_lshlrev_b32_e32 v118, 4, v122
	v_lshl_add_u64 v[116:117], s[10:11], 2, v[116:117]
	v_and_b32_e32 v184, 0x1f0, v118
	v_lshl_add_u64 v[116:117], v[116:117], 0, v[184:185]
	v_mov_b32_e32 v116, v248
	v_mov_b32_e32 v117, v249
	v_mov_b32_e32 v118, v250
	v_mov_b32_e32 v119, v251

; #define LAS __attribute__((address_space(3)))
;     __device__ __forceinline__ void operator()(AccT& acc, const pg8::Unit& u, int wr, int wc, int fr, int fq) const {
;     ...
;         if (wt_t < 256) *(LAS f32x4*)(wt + 4 * wt_t) = wreg;
;         asm volatile("s_waitcnt lgkmcnt(0)" ::: "memory"); __builtin_amdgcn_s_barrier(); asm volatile("" ::: "memory");
;         bf16_t* abase = ACT + (size_t)(u.pm * (FF / 64) + 2 * u.pn + (wc >> 1)) * 16384 + (8 * wr + (wc & 1)) * 512 + (((fr * 64 + 16 * fq) ^ ((fr >> 3) << 5)) >> 1);
; #pragma unroll
;         for (int n = 0; n < 2; ++n) {
;             asm volatile("" ::: "memory");
;             f32x4 w0[2], w1[2], w2[2], bb[2];
; #pragma unroll
;             for (int bj = 0; bj < 2; ++bj) { const LAS float* wp = wt + bj * 128 + cl + 4 * n;
;                 w0[bj] = *(const LAS f32x4*)(wp); w1[bj] = *(const LAS f32x4*)(wp + 256); w2[bj] = *(const LAS f32x4*)(wp + 512); bb[bj] = *(const LAS f32x4*)(wp + 768); }
; #pragma unroll
;             for (int ai = 0; ai < 2; ++ai) {
;                 const int blk = 2 * ai + wr;
;                 f32x4 e1[2], e2[2];
; #pragma unroll
;                 for (int bj = 0; bj < 2; ++bj) {
;                     f32x4 v62 = (f32x4){0.f, 0.f, 0.f, 0.f}, v63 = v62;
;                     if (blk > 0) { v62 = *(const LAS f32x4*)(tl + (((blk - 1) * 2 + 0) * 256 + 128 * bj + cl + 4 * n)); v63 = *(const LAS f32x4*)(tl + (((blk - 1) * 2 + 1) * 256 + 128 * bj + cl + 4 * n)); }
.LBB0_606:
	s_or_b64 exec, exec, s[10:11]
	s_and_saveexec_b64 s[10:11], s[8:9]
	s_cbranch_execz .LBB0_608
	v_lshl_add_u32 v96, v122, 4, 0
	v_add_u32_e32 v96, 0x26000, v96
	ds_write_b128 v96, v[116:119]
.LBB0_608:
	s_or_b64 exec, exec, s[10:11]
	s_waitcnt lgkmcnt(0)
	s_barrier
	v_add_u32_e32 v96, 0, v201
	v_add_u32_e32 v195, 0x26000, v96
	ds_read_b128 v[104:107], v195
	ds_read_b128 v[96:99], v195 offset:512
	ds_read_b128 v[108:111], v195 offset:1024
	ds_read_b128 v[100:103], v195 offset:1536
	ds_read_b128 v[132:135], v195 offset:2048
	ds_read_b128 v[116:119], v195 offset:2560
	ds_read_b128 v[136:139], v195 offset:3072
	ds_read_b128 v[120:123], v195 offset:3584
	s_cmp_gt_i32 s31, 0
	s_cselect_b64 s[8:9], -1, 0
	s_lshl_b32 s10, s31, 11
	s_add_i32 s93, s10, 0
	s_add_i32 s10, s93, 0x1f800
	s_add_i32 s11, s93, 0x1fc00
	s_cmp_lt_i32 s31, 1
	v_add_u32_e32 v184, s10, v201
	v_add_u32_e32 v202, s11, v201
	v_mov_b32_e32 v160, 0
	v_mov_b32_e32 v164, 0
	v_mov_b32_e32 v165, 0
	v_mov_b32_e32 v166, 0
	v_mov_b32_e32 v167, 0
	v_mov_b32_e32 v168, 0
	v_mov_b32_e32 v169, 0
	v_mov_b32_e32 v170, 0
	v_mov_b32_e32 v171, 0
	s_cbranch_scc1 .LBB0_610
	ds_read_b128 v[164:167], v184
	ds_read_b128 v[168:171], v202

; __global__ void __launch_bounds__(512, 2) hybrid_fwd(Args args) {
;     ...
;                 const bf16_t* ap = XB + (size_t)(bc * 64 + 16 * rt + c16) * 1024 + kh * 512 + 8 * kq;
;                 const int kb0 = kh * 512 + 8 * kq;
;                 f32x4 aacc = (f32x4){0.f, 0.f, 0.f, 0.f};
; #pragma unroll 4
;                 for (int ks = 0; ks < 16; ++ks) aacc = __builtin_amdgcn_mfma_f32_16x16x32_bf16(*(const bf16x8*)(ap + 32 * ks), *(const bf16x8*)(WinO + pg8::bimg_off(3072 + c16, kb0 + 32 * ks, 16)), aacc, 0, 0, 0);
; #pragma unroll
;                 for (int i = 0; i < 4; ++i) part[kh * 1024 + (16 * rt + 4 * kq + i) * 16 + c16] = aacc[i];
;                 __syncthreads();
.LBB0_977:
	s_or_b32 s9, s8, s12
	s_ashr_i32 s22, s9, 6
	s_ashr_i32 s23, s22, 31
	s_lshl_b64 s[22:23], s[22:23], 15
	s_add_u32 s22, s22, 0x600000
	s_addc_u32 s23, s23, 0
	v_lshl_add_u64 v[242:243], v[48:49], 0, s[22:23]
	v_lshl_add_u64 v[244:245], v[50:51], 0, s[22:23]
	global_load_dwordx4 v[174:177], v[72:73], off offset:-128
	global_load_dwordx4 v[178:181], v[72:73], off offset:-64
	global_load_dwordx4 v[182:185], v[72:73], off
	global_load_dwordx4 v[186:189], v[72:73], off offset:64
	global_load_dwordx4 v[190:193], v[242:243], off
	global_load_dwordx4 v[194:197], v[244:245], off
	s_add_i32 s9, s12, s8
	s_add_i32 s19, s9, 64
	s_ashr_i32 s22, s19, 6
	s_ashr_i32 s23, s22, 31
	s_lshl_b64 s[22:23], s[22:23], 15
	s_addk_i32 s9, 0x60
	v_lshl_add_u64 v[242:243], v[48:49], 0, s[22:23]
	s_ashr_i32 s24, s9, 6
	v_add_co_u32_e32 v242, vcc, s27, v242
	s_ashr_i32 s25, s24, 31
	s_nop 0
	v_addc_co_u32_e32 v243, vcc, 0, v243, vcc
	s_lshl_b64 s[24:25], s[24:25], 15
	global_load_dwordx4 v[198:201], v[242:243], off
	v_lshl_add_u64 v[244:245], v[50:51], 0, s[24:25]
	v_add_co_u32_e32 v244, vcc, 0x600000, v244
	s_addk_i32 s8, 0x80
	s_nop 0
	v_addc_co_u32_e32 v245, vcc, 0, v245, vcc
	global_load_dwordx4 v[204:207], v[244:245], off
	v_lshl_add_u64 v[72:73], v[72:73], 0, s[16:17]
	s_or_b32 s9, s8, s12
	s_ashr_i32 s22, s9, 6
	s_ashr_i32 s23, s22, 31
	s_lshl_b64 s[22:23], s[22:23], 15
	s_add_u32 s22, s22, 0x600000
	s_addc_u32 s23, s23, 0
	v_lshl_add_u64 v[242:243], v[48:49], 0, s[22:23]
	v_lshl_add_u64 v[244:245], v[50:51], 0, s[22:23]
	global_load_dwordx4 v[208:211], v[72:73], off offset:-128
	global_load_dwordx4 v[212:215], v[72:73], off offset:-64
	global_load_dwordx4 v[216:219], v[72:73], off
	global_load_dwordx4 v[222:225], v[72:73], off offset:64
	global_load_dwordx4 v[226:229], v[242:243], off
	global_load_dwordx4 v[230:233], v[244:245], off
	s_add_i32 s9, s12, s8
	s_add_i32 s19, s9, 64
	s_ashr_i32 s22, s19, 6
	s_ashr_i32 s23, s22, 31
	s_lshl_b64 s[22:23], s[22:23], 15
	s_addk_i32 s9, 0x60
	v_lshl_add_u64 v[242:243], v[48:49], 0, s[22:23]
	s_ashr_i32 s24, s9, 6
	v_add_co_u32_e32 v242, vcc, s27, v242
	s_ashr_i32 s25, s24, 31
	s_nop 0
	v_addc_co_u32_e32 v243, vcc, 0, v243, vcc
	s_lshl_b64 s[24:25], s[24:25], 15
	global_load_dwordx4 v[234:237], v[242:243], off
	v_lshl_add_u64 v[244:245], v[50:51], 0, s[24:25]
	v_add_co_u32_e32 v244, vcc, 0x600000, v244
	s_addk_i32 s8, 0x80
	s_nop 0
	v_addc_co_u32_e32 v245, vcc, 0, v245, vcc
	global_load_dwordx4 v[238:241], v[244:245], off
	v_lshl_add_u64 v[72:73], v[72:73], 0, s[16:17]
	s_waitcnt vmcnt(8)
	v_mfma_f32_16x16x32_bf16 v[0:3], v[174:177], v[190:193], v[0:3]
	v_mfma_f32_16x16x32_bf16 v[0:3], v[178:181], v[194:197], v[0:3]
	v_mfma_f32_16x16x32_bf16 v[0:3], v[182:185], v[198:201], v[0:3]
	v_mfma_f32_16x16x32_bf16 v[0:3], v[186:189], v[204:207], v[0:3]
	s_or_b32 s9, s8, s12
	s_ashr_i32 s22, s9, 6
	s_ashr_i32 s23, s22, 31
	s_lshl_b64 s[22:23], s[22:23], 15
	s_add_u32 s22, s22, 0x600000
	s_addc_u32 s23, s23, 0
	v_lshl_add_u64 v[242:243], v[48:49], 0, s[22:23]
	v_lshl_add_u64 v[244:245], v[50:51], 0, s[22:23]
	global_load_dwordx4 v[174:177], v[72:73], off offset:-128
	global_load_dwordx4 v[178:181], v[72:73], off offset:-64
	global_load_dwordx4 v[182:185], v[72:73], off
	global_load_dwordx4 v[186:189], v[72:73], off offset:64
	global_load_dwordx4 v[190:193], v[242:243], off
	global_load_dwordx4 v[194:197], v[244:245], off
	s_add_i32 s9, s12, s8
	s_add_i32 s19, s9, 64
	s_ashr_i32 s22, s19, 6
	s_ashr_i32 s23, s22, 31
	s_lshl_b64 s[22:23], s[22:23], 15
	s_addk_i32 s9, 0x60
	v_lshl_add_u64 v[242:243], v[48:49], 0, s[22:23]
	s_ashr_i32 s24, s9, 6
	v_add_co_u32_e32 v242, vcc, s27, v242
	s_ashr_i32 s25, s24, 31
	s_nop 0
	v_addc_co_u32_e32 v243, vcc, 0, v243, vcc
	s_lshl_b64 s[24:25], s[24:25], 15
	global_load_dwordx4 v[198:201], v[242:243], off
	v_lshl_add_u64 v[244:245], v[50:51], 0, s[24:25]
	v_add_co_u32_e32 v244, vcc, 0x600000, v244
	s_addk_i32 s8, 0x80
	s_nop 0
	v_addc_co_u32_e32 v245, vcc, 0, v245, vcc
	global_load_dwordx4 v[204:207], v[244:245], off
	v_lshl_add_u64 v[72:73], v[72:73], 0, s[16:17]
	s_waitcnt vmcnt(8)
	v_mfma_f32_16x16x32_bf16 v[0:3], v[208:211], v[226:229], v[0:3]
	v_mfma_f32_16x16x32_bf16 v[0:3], v[212:215], v[230:233], v[0:3]
	v_mfma_f32_16x16x32_bf16 v[0:3], v[216:219], v[234:237], v[0:3]
	v_mfma_f32_16x16x32_bf16 v[0:3], v[222:225], v[238:241], v[0:3]
	s_or_b32 s9, s8, s12
	s_ashr_i32 s22, s9, 6
	s_ashr_i32 s23, s22, 31
	s_lshl_b64 s[22:23], s[22:23], 15
	s_add_u32 s22, s22, 0x600000
	s_addc_u32 s23, s23, 0
	v_lshl_add_u64 v[242:243], v[48:49], 0, s[22:23]
	v_lshl_add_u64 v[244:245], v[50:51], 0, s[22:23]
	global_load_dwordx4 v[208:211], v[72:73], off offset:-128
	global_load_dwordx4 v[212:215], v[72:73], off offset:-64
	global_load_dwordx4 v[216:219], v[72:73], off
	global_load_dwordx4 v[222:225], v[72:73], off offset:64
	global_load_dwordx4 v[226:229], v[242:243], off
	global_load_dwordx4 v[230:233], v[244:245], off
	s_add_i32 s9, s12, s8
	s_add_i32 s19, s9, 64
	s_ashr_i32 s22, s19, 6
	s_ashr_i32 s23, s22, 31
	s_lshl_b64 s[22:23], s[22:23], 15
	s_addk_i32 s9, 0x60
	v_lshl_add_u64 v[242:243], v[48:49], 0, s[22:23]
	s_ashr_i32 s24, s9, 6
	v_add_co_u32_e32 v242, vcc, s27, v242
	s_ashr_i32 s25, s24, 31
	s_nop 0
	v_addc_co_u32_e32 v243, vcc, 0, v243, vcc
	s_lshl_b64 s[24:25], s[24:25], 15
	global_load_dwordx4 v[234:237], v[242:243], off
	v_lshl_add_u64 v[244:245], v[50:51], 0, s[24:25]
	v_add_co_u32_e32 v244, vcc, 0x600000, v244
	s_addk_i32 s8, 0x80
	s_nop 0
	v_addc_co_u32_e32 v245, vcc, 0, v245, vcc
	global_load_dwordx4 v[238:241], v[244:245], off
	v_lshl_add_u64 v[72:73], v[72:73], 0, s[16:17]
	s_waitcnt vmcnt(8)
	v_mfma_f32_16x16x32_bf16 v[0:3], v[174:177], v[190:193], v[0:3]
	v_mfma_f32_16x16x32_bf16 v[0:3], v[178:181], v[194:197], v[0:3]
	v_mfma_f32_16x16x32_bf16 v[0:3], v[182:185], v[198:201], v[0:3]
	v_mfma_f32_16x16x32_bf16 v[0:3], v[186:189], v[204:207], v[0:3]
	s_waitcnt vmcnt(0)
	v_mfma_f32_16x16x32_bf16 v[0:3], v[208:211], v[226:229], v[0:3]
	v_mfma_f32_16x16x32_bf16 v[0:3], v[212:215], v[230:233], v[0:3]
	v_mfma_f32_16x16x32_bf16 v[0:3], v[216:219], v[234:237], v[0:3]
	v_mfma_f32_16x16x32_bf16 v[0:3], v[222:225], v[238:241], v[0:3]
	s_cmpk_eq_i32 s8, 0x200
	s_nop 6
	ds_write2_b32 v107, v0, v1 offset1:16
	ds_write2_b32 v107, v2, v3 offset0:32 offset1:48
	s_waitcnt lgkmcnt(0)
	s_barrier
	s_and_saveexec_b64 s[22:23], s[6:7]
	s_cbranch_execz .LBB0_981
	s_mov_b64 s[24:25], 0
	v_mov_b32_e32 v0, v14
	v_mov_b32_e32 v1, v4

; #define PG8_WAIT_V(n) asm volatile("s_waitcnt vmcnt(" #n ")" ::: "memory")
; #define PG8_BAR __builtin_amdgcn_s_barrier()
; template <class Epi, bool HALO>
; __device__ __forceinline__ void gemm_phase(LAS unsigned char* lds, const Gemm g, const StaticOrder& S, const Epi& E) {
;     ...
;     f32x4 acc[2][2][4][2];
; #pragma unroll
;     for (int a = 0; a < 2; ++a)
; #pragma unroll
;         for (int b = 0; b < 2; ++b)
; #pragma unroll
;             for (int m = 0; m < 4; ++m)
; #pragma unroll
;                 for (int n = 0; n < 2; ++n) acc[a][b][m][n] = (f32x4){0.f, 0.f, 0.f, 0.f};
;     bf16x8 At[4][2], B0[2][2], B1[2][2];
;     const char* cA = A0 + (size_t)cur.pm * tstepA + (size_t)cur.pn * g.a_pn_off * 2; const char* cB = (const char*)g.Bt + (size_t)cur.pn * tstepB;
;     PG8_STAGE(PG8_SB(0, 0), cB, voffB); PG8_STAGE(PG8_SB(0, 1), cB + hstepB, voffB); PG8_STAGE(PG8_SA(0, 0), cA, voffA); PG8_STAGE(PG8_SA(0, 1), cA + hstepA, voffA);
;     if (wr == 1) PG8_BAR;
;     PG8_WAIT_V(2); PG8_BAR;
;     PG8_STAGE(PG8_SB(1, 0), cB + kstepB, voffB); PG8_STAGE(PG8_SA(1, 0), cA + kstep, voffA); PG8_STAGE(PG8_SB(1, 1), cB + hstepB + kstepB, voffB);
;     PG8_WAIT_V(6); PG8_BAR;
;     for (;;) {
;         const bool has_next = S.next(ui + 1, nxt);
;         const char* nA = has_next ? A0 + (size_t)nxt.pm * tstepA + (size_t)nxt.pn * g.a_pn_off * 2 : cA; const char* nB = has_next ? (const char*)g.Bt + (size_t)nxt.pn * tstepB : cB;
;         for (int t = 0; t < nt; t += 2) {
;             const bool last = (t == nt - 2);
;             const char* a1 = cA + (size_t)(t + 1) * kstep;
;             const char* a2 = last ? nA : cA + (size_t)(t + 2) * kstep; const char* b2 = last ? nB : cB + (size_t)(t + 2) * kstepB;
;             const char* a3 = a2 + kstep; const char* b3 = b2 + kstepB;
;             PG8_LDB(B0, 0, 0); PG8_LDB(B1, 0, 1); PG8_SCHED; PG8_LDA(At, 0, 0); PG8_STAGE(PG8_SA(1, 1), a1 + hstepA, voffA);
;     __device__ __forceinline__ void operator()(AccT& acc, const pg8::Unit& u, int wr, int wc, int fr, int fq) const {
;     ...
;         const int wt_t = (4 * wr + wc) * 64 + fq * 16 + fr;
;         f32x4 wreg = (f32x4){0.f, 0.f, 0.f, 0.f};
;         if (wt_t < 256) { const int kind = wt_t >> 6, hf = (wt_t & 63) >> 5, c = ((wt_t & 63) * 4) & 127;
;             wreg = *(const f32x4*)((kind < 3 ? cw + kind * FF2 : cb) + hf * FF + u.pn * 128 + c); }
.LBB0_1277:
	s_ashr_i32 s35, s34, 31
	s_lshl_b64 s[12:13], s[34:35], 19
	s_add_u32 s36, s52, s12
	s_addc_u32 s37, s53, s13
	s_and_b64 s[12:13], s[6:7], exec
	s_cselect_b32 s16, s37, s11
	s_cselect_b32 s17, s36, s10
	s_ashr_i32 s31, s30, 31
	s_lshl_b64 s[12:13], s[30:31], 19
	s_add_u32 s38, s48, s12
	s_addc_u32 s39, s49, s13
	s_and_b64 s[12:13], s[6:7], exec
	s_cselect_b32 s31, s39, s9
	s_cselect_b32 s35, s38, s8
	s_add_u32 s41, s8, 0x10000
	s_addc_u32 s42, s9, 0
	s_add_u32 s8, s10, 0x40080
	v_mov_b32_e32 v24, 0
	s_addc_u32 s9, s11, 0
	s_mov_b32 s43, -2
	v_mov_b32_e32 v25, v24
	v_mov_b32_e32 v26, v24
	v_mov_b32_e32 v27, v24
	v_mov_b32_e32 v76, v24
	v_mov_b32_e32 v77, v24
	v_mov_b32_e32 v78, v24
	v_mov_b32_e32 v79, v24
	v_mov_b32_e32 v0, v24
	v_mov_b32_e32 v1, v24
	v_mov_b32_e32 v2, v24
	v_mov_b32_e32 v3, v24
	v_mov_b32_e32 v56, v24
	v_mov_b32_e32 v57, v24
	v_mov_b32_e32 v58, v24
	v_mov_b32_e32 v59, v24
	v_mov_b32_e32 v4, v24
	v_mov_b32_e32 v5, v24
	v_mov_b32_e32 v6, v24
	v_mov_b32_e32 v7, v24
	v_mov_b32_e32 v60, v24
	v_mov_b32_e32 v61, v24
	v_mov_b32_e32 v62, v24
	v_mov_b32_e32 v63, v24
	v_mov_b32_e32 v16, v24
	v_mov_b32_e32 v17, v24
	v_mov_b32_e32 v18, v24
	v_mov_b32_e32 v19, v24
	v_mov_b32_e32 v80, v24
	v_mov_b32_e32 v81, v24
	v_mov_b32_e32 v82, v24
	v_mov_b32_e32 v83, v24
	v_mov_b32_e32 v28, v24
	v_mov_b32_e32 v29, v24
	v_mov_b32_e32 v30, v24
	v_mov_b32_e32 v31, v24
	v_mov_b32_e32 v88, v24
	v_mov_b32_e32 v89, v24
	v_mov_b32_e32 v90, v24
	v_mov_b32_e32 v91, v24
	v_mov_b32_e32 v8, v24
	v_mov_b32_e32 v9, v24
	v_mov_b32_e32 v10, v24
	v_mov_b32_e32 v11, v24
	v_mov_b32_e32 v64, v24
	v_mov_b32_e32 v65, v24
	v_mov_b32_e32 v66, v24
	v_mov_b32_e32 v67, v24
	v_mov_b32_e32 v12, v24
	v_mov_b32_e32 v13, v24
	v_mov_b32_e32 v14, v24
	v_mov_b32_e32 v15, v24
	v_mov_b32_e32 v68, v24
	v_mov_b32_e32 v69, v24
	v_mov_b32_e32 v70, v24
	v_mov_b32_e32 v71, v24
	v_mov_b32_e32 v20, v24
	v_mov_b32_e32 v21, v24
	v_mov_b32_e32 v22, v24
	v_mov_b32_e32 v23, v24
	v_mov_b32_e32 v84, v24
	v_mov_b32_e32 v85, v24
	v_mov_b32_e32 v86, v24
	v_mov_b32_e32 v87, v24
	v_mov_b32_e32 v48, v24
	v_mov_b32_e32 v49, v24
	v_mov_b32_e32 v50, v24
	v_mov_b32_e32 v51, v24
	v_mov_b32_e32 v92, v24
	v_mov_b32_e32 v93, v24
	v_mov_b32_e32 v94, v24
	v_mov_b32_e32 v95, v24
	v_mov_b32_e32 v32, v24
	v_mov_b32_e32 v33, v24
	v_mov_b32_e32 v34, v24
	v_mov_b32_e32 v35, v24
	v_mov_b32_e32 v112, v24
	v_mov_b32_e32 v113, v24
	v_mov_b32_e32 v114, v24
	v_mov_b32_e32 v115, v24
	v_mov_b32_e32 v36, v24
	v_mov_b32_e32 v37, v24
	v_mov_b32_e32 v38, v24
	v_mov_b32_e32 v39, v24
	v_mov_b32_e32 v124, v24
	v_mov_b32_e32 v125, v24
	v_mov_b32_e32 v126, v24
	v_mov_b32_e32 v127, v24
	v_mov_b32_e32 v72, v24
	v_mov_b32_e32 v73, v24
	v_mov_b32_e32 v74, v24
	v_mov_b32_e32 v75, v24
	v_mov_b32_e32 v96, v24
	v_mov_b32_e32 v97, v24
	v_mov_b32_e32 v98, v24
	v_mov_b32_e32 v99, v24
	v_mov_b32_e32 v52, v24
	v_mov_b32_e32 v53, v24
	v_mov_b32_e32 v54, v24
	v_mov_b32_e32 v55, v24
	v_mov_b32_e32 v108, v24
	v_mov_b32_e32 v109, v24
	v_mov_b32_e32 v110, v24
	v_mov_b32_e32 v111, v24
	v_mov_b32_e32 v40, v24
	v_mov_b32_e32 v41, v24
	v_mov_b32_e32 v42, v24
	v_mov_b32_e32 v43, v24
	v_mov_b32_e32 v128, v24
	v_mov_b32_e32 v129, v24
	v_mov_b32_e32 v130, v24
	v_mov_b32_e32 v131, v24
	v_mov_b32_e32 v44, v24
	v_mov_b32_e32 v45, v24
	v_mov_b32_e32 v46, v24
	v_mov_b32_e32 v47, v24
	v_mov_b32_e32 v140, v24
	v_mov_b32_e32 v141, v24
	v_mov_b32_e32 v142, v24
	v_mov_b32_e32 v143, v24
	v_mov_b32_e32 v100, v24
	v_mov_b32_e32 v101, v24
	v_mov_b32_e32 v102, v24
	v_mov_b32_e32 v103, v24
	v_mov_b32_e32 v104, v24
	v_mov_b32_e32 v105, v24
	v_mov_b32_e32 v106, v24
	v_mov_b32_e32 v107, v24
	v_readfirstlane_b32 s95, v220
	s_lshr_b32 s95, s95, 6
	s_cmp_gt_u32 s95, 3
	s_cbranch_scc1 .Lwp12_skip
	s_mul_i32 s96, s95, 0x5800
	s_add_u32 s96, s59, s96
	s_addc_u32 s97, s60, 0
	s_cmp_lt_u32 s95, 3
	s_cselect_b32 s96, s96, s61
	s_cselect_b32 s97, s97, s62
	s_lshl_b32 s95, s40, 9
	s_add_u32 s96, s96, s95
	s_addc_u32 s97, s97, 0
	v_and_b32_e32 v244, 63, v220
	v_lshrrev_b32_e32 v245, 5, v244
	v_mul_u32_u24_e32 v245, 0x2c00, v245
	v_and_b32_e32 v244, 31, v244
	v_lshl_add_u32 v244, v244, 4, v245
	global_load_dwordx4 v[248:251], v244, s[96:97]
.Lwp12_skip:
.LBB0_1278:
	ds_read_b128 v[116:119], v222
	ds_read_b128 v[120:123], v222 offset:1024
	ds_read_b128 v[132:135], v222 offset:2048
	ds_read_b128 v[136:139], v222 offset:3072
	ds_read_b128 v[144:147], v223
	ds_read_b128 v[148:151], v223 offset:1024
	ds_read_b128 v[152:155], v223 offset:2048
	ds_read_b128 v[156:159], v223 offset:3072
	s_add_u32 s10, s8, 0xfffc0080
	s_addc_u32 s11, s9, -1
	s_cmp_eq_u32 s43, 12
	s_cselect_b32 s13, s16, s11
	s_cselect_b32 s12, s17, s10
	s_cselect_b32 s11, s31, s42
	s_cselect_b32 s10, s35, s41
	v_lshl_add_u64 v[210:211], s[8:9], 0, v[186:187]
	s_add_i32 m0, s54, 0xc000
	ds_read_b128 v[160:163], v224
	ds_read_b128 v[164:167], v224 offset:1024
	ds_read_b128 v[168:171], v224 offset:2048
	ds_read_b128 v[172:175], v224 offset:3072
	ds_read_b128 v[194:197], v224 offset:4096
	ds_read_b128 v[198:201], v224 offset:5120
	ds_read_b128 v[202:205], v224 offset:6144
	ds_read_b128 v[206:209], v224 offset:7168
	global_load_lds_dwordx4 v[210:211], off
	v_lshl_add_u64 v[210:211], s[8:9], 0, v[188:189]
	s_add_i32 m0, s54, 0xe000
	s_nop 0
	global_load_lds_dwordx4 v[210:211], off
	s_waitcnt vmcnt(8)
	s_waitcnt lgkmcnt(0)
	s_barrier
; #define PG8_STAGE(bufoff, gbase, voff) do { _Pragma("unroll") for (int _i = 0; _i < 2; ++_i) \
;         __builtin_amdgcn_global_load_lds((const unsigned*)((const char*)(gbase) + (voff)[_i]), (LAS unsigned*)(lds + (bufoff) + ldsw + _i * 8192), 16, 0, 0); } while (0)
; #define PG8_LDA(dst, b, h) do { _Pragma("unroll") for (int m = 0; m < 4; ++m) _Pragma("unroll") for (int k = 0; k < 2; ++k) dst[m][k] = *(const LAS bf16x8*)(lds + PG8_SA(b, h) + aoff + m * 2048 + k * 1024); } while (0)
; #define PG8_MMA(ai, bj, At, Bt) do { __builtin_amdgcn_s_setprio(1); _Pragma("unroll") for (int m = 0; m < 4; ++m) _Pragma("unroll") for (int n = 0; n < 2; ++n) _Pragma("unroll") for (int k = 0; k < 2; ++k) \
;         acc[ai][bj][m][n] = __builtin_amdgcn_mfma_f32_16x16x32_bf16(Bt[n][k], At[m][k], acc[ai][bj][m][n], 0, 0, 0); __builtin_amdgcn_s_setprio(0); } while (0)
; #define PG8_WAIT_V(n) asm volatile("s_waitcnt vmcnt(" #n ")" ::: "memory")
; #define PG8_WAIT_L(n) asm volatile("s_waitcnt lgkmcnt(" #n ")" ::: "memory")
; #define PG8_BAR __builtin_amdgcn_s_barrier()
; #define PG8_SCHED __builtin_amdgcn_sched_barrier(0)
; template <class Epi, bool HALO>
; __device__ __forceinline__ void gemm_phase(LAS unsigned char* lds, const Gemm g, const StaticOrder& S, const Epi& E) {
;     ...
;             PG8_WAIT_V(8); PG8_WAIT_L(0); PG8_BAR; PG8_MMA(0, 0, At, B0); PG8_MMA(0, 1, At, B1); PG8_BAR; PG8_SCHED;
;             PG8_LDA(At, 0, 1); PG8_STAGE(PG8_SB(0, 0), b2, voffB); PG8_STAGE(PG8_SB(0, 1), b2 + hstepB, voffB); PG8_STAGE(PG8_SA(0, 0), a2, voffA);
;             PG8_WAIT_V(8); PG8_WAIT_L(0); PG8_BAR; PG8_MMA(1, 0, At, B0); PG8_MMA(1, 1, At, B1); PG8_BAR; PG8_SCHED;
	s_setprio 1
	s_waitcnt lgkmcnt(0)
	v_mfma_f32_16x16x32_bf16 v[104:107], v[116:119], v[160:163], v[104:107]
	v_mfma_f32_16x16x32_bf16 v[100:103], v[132:135], v[160:163], v[100:103]
	v_mfma_f32_16x16x32_bf16 v[140:143], v[116:119], v[168:171], v[140:143]
	v_mfma_f32_16x16x32_bf16 v[44:47], v[132:135], v[168:171], v[44:47]
	v_mfma_f32_16x16x32_bf16 v[128:131], v[116:119], v[194:197], v[128:131]
	v_mfma_f32_16x16x32_bf16 v[40:43], v[132:135], v[194:197], v[40:43]
	v_mfma_f32_16x16x32_bf16 v[108:111], v[116:119], v[202:205], v[108:111]
	v_mfma_f32_16x16x32_bf16 v[52:55], v[132:135], v[202:205], v[52:55]
	v_mfma_f32_16x16x32_bf16 v[104:107], v[120:123], v[164:167], v[104:107]
	v_mfma_f32_16x16x32_bf16 v[100:103], v[136:139], v[164:167], v[100:103]
	v_mfma_f32_16x16x32_bf16 v[140:143], v[120:123], v[172:175], v[140:143]
	v_mfma_f32_16x16x32_bf16 v[44:47], v[136:139], v[172:175], v[44:47]
	v_mfma_f32_16x16x32_bf16 v[128:131], v[120:123], v[198:201], v[128:131]
	v_mfma_f32_16x16x32_bf16 v[40:43], v[136:139], v[198:201], v[40:43]
	v_mfma_f32_16x16x32_bf16 v[108:111], v[120:123], v[206:209], v[108:111]
	v_mfma_f32_16x16x32_bf16 v[52:55], v[136:139], v[206:209], v[52:55]
	s_setprio 0
	s_setprio 1
	v_mfma_f32_16x16x32_bf16 v[96:99], v[144:147], v[160:163], v[96:99]
	v_mfma_f32_16x16x32_bf16 v[72:75], v[152:155], v[160:163], v[72:75]
	v_mfma_f32_16x16x32_bf16 v[124:127], v[144:147], v[168:171], v[124:127]
	v_mfma_f32_16x16x32_bf16 v[36:39], v[152:155], v[168:171], v[36:39]
	v_mfma_f32_16x16x32_bf16 v[112:115], v[144:147], v[194:197], v[112:115]
	v_mfma_f32_16x16x32_bf16 v[32:35], v[152:155], v[194:197], v[32:35]
	v_mfma_f32_16x16x32_bf16 v[92:95], v[144:147], v[202:205], v[92:95]
	v_mfma_f32_16x16x32_bf16 v[48:51], v[152:155], v[202:205], v[48:51]
	v_mfma_f32_16x16x32_bf16 v[96:99], v[148:151], v[164:167], v[96:99]
	v_mfma_f32_16x16x32_bf16 v[72:75], v[156:159], v[164:167], v[72:75]
	v_mfma_f32_16x16x32_bf16 v[124:127], v[148:151], v[172:175], v[124:127]
	v_mfma_f32_16x16x32_bf16 v[36:39], v[156:159], v[172:175], v[36:39]
	v_mfma_f32_16x16x32_bf16 v[112:115], v[148:151], v[198:201], v[112:115]
	v_mfma_f32_16x16x32_bf16 v[32:35], v[156:159], v[198:201], v[32:35]
	v_mfma_f32_16x16x32_bf16 v[92:95], v[148:151], v[206:209], v[92:95]
	v_mfma_f32_16x16x32_bf16 v[48:51], v[156:159], v[206:209], v[48:51]
	s_setprio 0
	s_barrier
	s_add_i32 s44, s70, s51
	v_lshl_add_u64 v[210:211], s[10:11], 0, v[176:177]
	s_mov_b32 m0, s44
	ds_read_b128 v[160:163], v224 offset:16384
	ds_read_b128 v[164:167], v224 offset:17408
	ds_read_b128 v[168:171], v224 offset:18432
	ds_read_b128 v[172:175], v224 offset:19456
	ds_read_b128 v[194:197], v224 offset:20480
	ds_read_b128 v[198:201], v224 offset:21504
	ds_read_b128 v[202:205], v224 offset:22528
	ds_read_b128 v[206:209], v224 offset:23552
	global_load_lds_dwordx4 v[210:211], off
	s_add_i32 m0, s44, 0x2000
	s_add_u32 s44, s10, 0x4000
	v_lshl_add_u64 v[210:211], s[10:11], 0, v[180:181]
	s_addc_u32 s45, s11, 0
	s_add_i32 s91, s71, s51
	global_load_lds_dwordx4 v[210:211], off
	v_lshl_add_u64 v[210:211], s[44:45], 0, v[176:177]
	s_mov_b32 m0, s91
	v_lshl_add_u64 v[212:213], s[12:13], 0, v[182:183]
	global_load_lds_dwordx4 v[210:211], off
	v_lshl_add_u64 v[210:211], s[44:45], 0, v[180:181]
	s_add_i32 m0, s91, 0x2000
	s_nop 0
	global_load_lds_dwordx4 v[210:211], off
	v_lshl_add_u64 v[210:211], s[12:13], 0, v[178:179]
	s_mov_b32 m0, s54
	s_nop 0
	global_load_lds_dwordx4 v[210:211], off
	s_mov_b32 m0, s55
	s_nop 0
	global_load_lds_dwordx4 v[212:213], off
	s_waitcnt vmcnt(8)
	s_waitcnt lgkmcnt(0)
	s_barrier
	s_setprio 1
	s_waitcnt lgkmcnt(0)
	v_mfma_f32_16x16x32_bf16 v[84:87], v[116:119], v[160:163], v[84:87]
	v_mfma_f32_16x16x32_bf16 v[20:23], v[132:135], v[160:163], v[20:23]
	v_mfma_f32_16x16x32_bf16 v[68:71], v[116:119], v[168:171], v[68:71]
	v_mfma_f32_16x16x32_bf16 v[12:15], v[132:135], v[168:171], v[12:15]
	v_mfma_f32_16x16x32_bf16 v[64:67], v[116:119], v[194:197], v[64:67]
	v_mfma_f32_16x16x32_bf16 v[8:11], v[132:135], v[194:197], v[8:11]
	v_mfma_f32_16x16x32_bf16 v[88:91], v[116:119], v[202:205], v[88:91]
	v_mfma_f32_16x16x32_bf16 v[28:31], v[132:135], v[202:205], v[28:31]
	v_mfma_f32_16x16x32_bf16 v[84:87], v[120:123], v[164:167], v[84:87]
	v_mfma_f32_16x16x32_bf16 v[20:23], v[136:139], v[164:167], v[20:23]
	v_mfma_f32_16x16x32_bf16 v[68:71], v[120:123], v[172:175], v[68:71]
	v_mfma_f32_16x16x32_bf16 v[12:15], v[136:139], v[172:175], v[12:15]
	v_mfma_f32_16x16x32_bf16 v[64:67], v[120:123], v[198:201], v[64:67]
	v_mfma_f32_16x16x32_bf16 v[8:11], v[136:139], v[198:201], v[8:11]
	v_mfma_f32_16x16x32_bf16 v[88:91], v[120:123], v[206:209], v[88:91]
	v_mfma_f32_16x16x32_bf16 v[28:31], v[136:139], v[206:209], v[28:31]
	s_setprio 0
	s_setprio 1
	v_mfma_f32_16x16x32_bf16 v[80:83], v[144:147], v[160:163], v[80:83]
	v_mfma_f32_16x16x32_bf16 v[16:19], v[152:155], v[160:163], v[16:19]
	v_mfma_f32_16x16x32_bf16 v[60:63], v[144:147], v[168:171], v[60:63]
	v_mfma_f32_16x16x32_bf16 v[4:7], v[152:155], v[168:171], v[4:7]
	v_mfma_f32_16x16x32_bf16 v[56:59], v[144:147], v[194:197], v[56:59]
	v_mfma_f32_16x16x32_bf16 v[0:3], v[152:155], v[194:197], v[0:3]
	v_mfma_f32_16x16x32_bf16 v[76:79], v[144:147], v[202:205], v[76:79]
	v_mfma_f32_16x16x32_bf16 v[24:27], v[152:155], v[202:205], v[24:27]
	v_mfma_f32_16x16x32_bf16 v[80:83], v[148:151], v[164:167], v[80:83]
	v_mfma_f32_16x16x32_bf16 v[16:19], v[156:159], v[164:167], v[16:19]
	v_mfma_f32_16x16x32_bf16 v[60:63], v[148:151], v[172:175], v[60:63]
	v_mfma_f32_16x16x32_bf16 v[4:7], v[156:159], v[172:175], v[4:7]
	v_mfma_f32_16x16x32_bf16 v[56:59], v[148:151], v[198:201], v[56:59]
	v_mfma_f32_16x16x32_bf16 v[0:3], v[156:159], v[198:201], v[0:3]
	v_mfma_f32_16x16x32_bf16 v[76:79], v[148:151], v[206:209], v[76:79]
	v_mfma_f32_16x16x32_bf16 v[24:27], v[156:159], v[206:209], v[24:27]
	s_setprio 0
	s_barrier
; #define PG8_STAGE(bufoff, gbase, voff) do { _Pragma("unroll") for (int _i = 0; _i < 2; ++_i) \
;         __builtin_amdgcn_global_load_lds((const unsigned*)((const char*)(gbase) + (voff)[_i]), (LAS unsigned*)(lds + (bufoff) + ldsw + _i * 8192), 16, 0, 0); } while (0)
; #define PG8_LDA(dst, b, h) do { _Pragma("unroll") for (int m = 0; m < 4; ++m) _Pragma("unroll") for (int k = 0; k < 2; ++k) dst[m][k] = *(const LAS bf16x8*)(lds + PG8_SA(b, h) + aoff + m * 2048 + k * 1024); } while (0)
; #define PG8_LDB(dst, b, h) do { _Pragma("unroll") for (int n = 0; n < 2; ++n) _Pragma("unroll") for (int k = 0; k < 2; ++k) dst[n][k] = *(const LAS bf16x8*)(lds + PG8_SB(b, h) + boff + n * 2048 + k * 1024); } while (0)
; #define PG8_MMA(ai, bj, At, Bt) do { __builtin_amdgcn_s_setprio(1); _Pragma("unroll") for (int m = 0; m < 4; ++m) _Pragma("unroll") for (int n = 0; n < 2; ++n) _Pragma("unroll") for (int k = 0; k < 2; ++k) \
;         acc[ai][bj][m][n] = __builtin_amdgcn_mfma_f32_16x16x32_bf16(Bt[n][k], At[m][k], acc[ai][bj][m][n], 0, 0, 0); __builtin_amdgcn_s_setprio(0); } while (0)
; #define PG8_WAIT_V(n) asm volatile("s_waitcnt vmcnt(" #n ")" ::: "memory")
; #define PG8_WAIT_L(n) asm volatile("s_waitcnt lgkmcnt(" #n ")" ::: "memory")
; #define PG8_BAR __builtin_amdgcn_s_barrier()
; #define PG8_SCHED __builtin_amdgcn_sched_barrier(0)
; template <class Epi, bool HALO>
; __device__ __forceinline__ void gemm_phase(LAS unsigned char* lds, const Gemm g, const StaticOrder& S, const Epi& E) {
;     ...
;             PG8_LDB(B0, 1, 0); PG8_LDB(B1, 1, 1); PG8_SCHED; PG8_LDA(At, 1, 0); PG8_STAGE(PG8_SA(0, 1), a2 + hstepA, voffA);
;             PG8_WAIT_V(8); PG8_WAIT_L(0); PG8_BAR; PG8_MMA(0, 0, At, B0); PG8_MMA(0, 1, At, B1); PG8_BAR; PG8_SCHED;
;             PG8_LDA(At, 1, 1); PG8_STAGE(PG8_SB(1, 0), b3, voffB); PG8_STAGE(PG8_SB(1, 1), b3 + hstepB, voffB); PG8_STAGE(PG8_SA(1, 0), a3, voffA);
	s_add_i32 s44, 0, 0x18000
	s_add_i32 s45, 0, 0x1c000
	v_add_u32_e32 v136, s44, v221
	v_add_u32_e32 v156, s45, v221
	ds_read_b128 v[116:119], v136
	ds_read_b128 v[120:123], v136 offset:1024
	ds_read_b128 v[132:135], v136 offset:2048
	ds_read_b128 v[136:139], v136 offset:3072
	ds_read_b128 v[144:147], v156
	ds_read_b128 v[148:151], v156 offset:1024
	ds_read_b128 v[152:155], v156 offset:2048
	ds_read_b128 v[156:159], v156 offset:3072
	s_add_u32 s12, s12, 0x40000
	s_addc_u32 s13, s13, 0
	s_mov_b32 m0, s56
	v_lshl_add_u64 v[214:215], s[12:13], 0, v[178:179]
	ds_read_b128 v[160:163], v224 offset:32768
	ds_read_b128 v[164:167], v224 offset:33792
	ds_read_b128 v[168:171], v224 offset:34816
	ds_read_b128 v[172:175], v224 offset:35840
	ds_read_b128 v[194:197], v224 offset:36864
	ds_read_b128 v[198:201], v224 offset:37888
	ds_read_b128 v[202:205], v224 offset:38912
	ds_read_b128 v[206:209], v224 offset:39936
	global_load_lds_dwordx4 v[214:215], off
	v_lshl_add_u64 v[214:215], s[12:13], 0, v[182:183]
	s_mov_b32 m0, s57
	s_nop 0
	global_load_lds_dwordx4 v[214:215], off
	s_waitcnt vmcnt(8)
	s_waitcnt lgkmcnt(0)
	s_barrier
	s_setprio 1
	s_waitcnt lgkmcnt(0)
	v_mfma_f32_16x16x32_bf16 v[104:107], v[116:119], v[160:163], v[104:107]
	v_mfma_f32_16x16x32_bf16 v[100:103], v[132:135], v[160:163], v[100:103]
	v_mfma_f32_16x16x32_bf16 v[140:143], v[116:119], v[168:171], v[140:143]
	v_mfma_f32_16x16x32_bf16 v[44:47], v[132:135], v[168:171], v[44:47]
	v_mfma_f32_16x16x32_bf16 v[128:131], v[116:119], v[194:197], v[128:131]
	v_mfma_f32_16x16x32_bf16 v[40:43], v[132:135], v[194:197], v[40:43]
	v_mfma_f32_16x16x32_bf16 v[108:111], v[116:119], v[202:205], v[108:111]
	v_mfma_f32_16x16x32_bf16 v[52:55], v[132:135], v[202:205], v[52:55]
	v_mfma_f32_16x16x32_bf16 v[104:107], v[120:123], v[164:167], v[104:107]
	v_mfma_f32_16x16x32_bf16 v[100:103], v[136:139], v[164:167], v[100:103]
	v_mfma_f32_16x16x32_bf16 v[140:143], v[120:123], v[172:175], v[140:143]
	v_mfma_f32_16x16x32_bf16 v[44:47], v[136:139], v[172:175], v[44:47]
	v_mfma_f32_16x16x32_bf16 v[128:131], v[120:123], v[198:201], v[128:131]
	v_mfma_f32_16x16x32_bf16 v[40:43], v[136:139], v[198:201], v[40:43]
	v_mfma_f32_16x16x32_bf16 v[108:111], v[120:123], v[206:209], v[108:111]
	v_mfma_f32_16x16x32_bf16 v[52:55], v[136:139], v[206:209], v[52:55]
	s_setprio 0
	s_setprio 1
	v_mfma_f32_16x16x32_bf16 v[96:99], v[144:147], v[160:163], v[96:99]
	v_mfma_f32_16x16x32_bf16 v[72:75], v[152:155], v[160:163], v[72:75]
	v_mfma_f32_16x16x32_bf16 v[124:127], v[144:147], v[168:171], v[124:127]
	v_mfma_f32_16x16x32_bf16 v[36:39], v[152:155], v[168:171], v[36:39]
	v_mfma_f32_16x16x32_bf16 v[112:115], v[144:147], v[194:197], v[112:115]
	v_mfma_f32_16x16x32_bf16 v[32:35], v[152:155], v[194:197], v[32:35]
	v_mfma_f32_16x16x32_bf16 v[92:95], v[144:147], v[202:205], v[92:95]
	v_mfma_f32_16x16x32_bf16 v[48:51], v[152:155], v[202:205], v[48:51]
	v_mfma_f32_16x16x32_bf16 v[96:99], v[148:151], v[164:167], v[96:99]
	v_mfma_f32_16x16x32_bf16 v[72:75], v[156:159], v[164:167], v[72:75]
	v_mfma_f32_16x16x32_bf16 v[124:127], v[148:151], v[172:175], v[124:127]
	v_mfma_f32_16x16x32_bf16 v[36:39], v[156:159], v[172:175], v[36:39]
	v_mfma_f32_16x16x32_bf16 v[112:115], v[148:151], v[198:201], v[112:115]
	v_mfma_f32_16x16x32_bf16 v[32:35], v[156:159], v[198:201], v[32:35]
	v_mfma_f32_16x16x32_bf16 v[92:95], v[148:151], v[206:209], v[92:95]
	v_mfma_f32_16x16x32_bf16 v[48:51], v[156:159], v[206:209], v[48:51]
	s_setprio 0
	s_barrier
	s_add_u32 s12, s10, 0x8000
	s_addc_u32 s13, s11, 0
	s_add_i32 s44, s44, s51
	v_lshl_add_u64 v[214:215], s[12:13], 0, v[176:177]
	s_mov_b32 m0, s44
	ds_read_b128 v[160:163], v224 offset:49152
	ds_read_b128 v[164:167], v224 offset:50176
	ds_read_b128 v[168:171], v224 offset:51200
	ds_read_b128 v[172:175], v224 offset:52224
	ds_read_b128 v[194:197], v224 offset:53248
	ds_read_b128 v[198:201], v224 offset:54272
	ds_read_b128 v[202:205], v224 offset:55296
	ds_read_b128 v[206:209], v224 offset:56320
	global_load_lds_dwordx4 v[214:215], off
	s_add_i32 m0, s44, 0x2000
	s_add_u32 s10, s10, 0xc000
	v_lshl_add_u64 v[214:215], s[12:13], 0, v[180:181]
	s_addc_u32 s11, s11, 0
	s_add_i32 s12, s45, s51
	global_load_lds_dwordx4 v[214:215], off
	v_lshl_add_u64 v[214:215], s[10:11], 0, v[176:177]
	s_mov_b32 m0, s12
	v_lshl_add_u64 v[210:211], v[210:211], 0, s[26:27]
	global_load_lds_dwordx4 v[214:215], off
	v_lshl_add_u64 v[214:215], s[10:11], 0, v[180:181]
	s_add_i32 m0, s12, 0x2000
	s_nop 0
	global_load_lds_dwordx4 v[214:215], off
	s_mov_b32 m0, s66
	s_nop 0
	global_load_lds_dwordx4 v[210:211], off
	v_lshl_add_u64 v[210:211], v[212:213], 0, s[26:27]
	s_mov_b32 m0, s67
	s_nop 0
	global_load_lds_dwordx4 v[210:211], off
	s_waitcnt vmcnt(8)
	s_waitcnt lgkmcnt(0)
	s_barrier
; #define PG8_MMA(ai, bj, At, Bt) do { __builtin_amdgcn_s_setprio(1); _Pragma("unroll") for (int m = 0; m < 4; ++m) _Pragma("unroll") for (int n = 0; n < 2; ++n) _Pragma("unroll") for (int k = 0; k < 2; ++k) \
;         acc[ai][bj][m][n] = __builtin_amdgcn_mfma_f32_16x16x32_bf16(Bt[n][k], At[m][k], acc[ai][bj][m][n], 0, 0, 0); __builtin_amdgcn_s_setprio(0); } while (0)
; #define PG8_WAIT_V(n) asm volatile("s_waitcnt vmcnt(" #n ")" ::: "memory")
; #define PG8_WAIT_L(n) asm volatile("s_waitcnt lgkmcnt(" #n ")" ::: "memory")
; #define PG8_BAR __builtin_amdgcn_s_barrier()
; #define PG8_SCHED __builtin_amdgcn_sched_barrier(0)
; template <class Epi, bool HALO>
; __device__ __forceinline__ void gemm_phase(LAS unsigned char* lds, const Gemm g, const StaticOrder& S, const Epi& E) {
;     ...
;             PG8_WAIT_V(8); PG8_WAIT_L(0); PG8_BAR; PG8_MMA(1, 0, At, B0); PG8_MMA(1, 1, At, B1); PG8_BAR; PG8_SCHED;
;         }
;         if (wr == 0) PG8_BAR;
;     __device__ __forceinline__ void operator()(AccT& acc, const pg8::Unit& u, int wr, int wc, int fr, int fq) const {
;     ...
;         const int wt_t = (4 * wr + wc) * 64 + fq * 16 + fr;
;         f32x4 wreg = (f32x4){0.f, 0.f, 0.f, 0.f};
;         if (wt_t < 256) { const int kind = wt_t >> 6, hf = (wt_t & 63) >> 5, c = ((wt_t & 63) * 4) & 127;
;             wreg = *(const f32x4*)((kind < 3 ? cw + kind * FF2 : cb) + hf * FF + u.pn * 128 + c); }
	s_setprio 1
	s_waitcnt lgkmcnt(0)
	v_mfma_f32_16x16x32_bf16 v[84:87], v[116:119], v[160:163], v[84:87]
	v_mfma_f32_16x16x32_bf16 v[20:23], v[132:135], v[160:163], v[20:23]
	v_mfma_f32_16x16x32_bf16 v[68:71], v[116:119], v[168:171], v[68:71]
	v_mfma_f32_16x16x32_bf16 v[12:15], v[132:135], v[168:171], v[12:15]
	v_mfma_f32_16x16x32_bf16 v[64:67], v[116:119], v[194:197], v[64:67]
	v_mfma_f32_16x16x32_bf16 v[8:11], v[132:135], v[194:197], v[8:11]
	v_mfma_f32_16x16x32_bf16 v[88:91], v[116:119], v[202:205], v[88:91]
	v_mfma_f32_16x16x32_bf16 v[28:31], v[132:135], v[202:205], v[28:31]
	v_mfma_f32_16x16x32_bf16 v[84:87], v[120:123], v[164:167], v[84:87]
	v_mfma_f32_16x16x32_bf16 v[20:23], v[136:139], v[164:167], v[20:23]
	v_mfma_f32_16x16x32_bf16 v[68:71], v[120:123], v[172:175], v[68:71]
	v_mfma_f32_16x16x32_bf16 v[12:15], v[136:139], v[172:175], v[12:15]
	v_mfma_f32_16x16x32_bf16 v[64:67], v[120:123], v[198:201], v[64:67]
	v_mfma_f32_16x16x32_bf16 v[8:11], v[136:139], v[198:201], v[8:11]
	v_mfma_f32_16x16x32_bf16 v[88:91], v[120:123], v[206:209], v[88:91]
	v_mfma_f32_16x16x32_bf16 v[28:31], v[136:139], v[206:209], v[28:31]
	s_setprio 0
	s_setprio 1
	v_mfma_f32_16x16x32_bf16 v[80:83], v[144:147], v[160:163], v[80:83]
	v_mfma_f32_16x16x32_bf16 v[16:19], v[152:155], v[160:163], v[16:19]
	v_mfma_f32_16x16x32_bf16 v[60:63], v[144:147], v[168:171], v[60:63]
	v_mfma_f32_16x16x32_bf16 v[4:7], v[152:155], v[168:171], v[4:7]
	v_mfma_f32_16x16x32_bf16 v[56:59], v[144:147], v[194:197], v[56:59]
	v_mfma_f32_16x16x32_bf16 v[0:3], v[152:155], v[194:197], v[0:3]
	v_mfma_f32_16x16x32_bf16 v[76:79], v[144:147], v[202:205], v[76:79]
	v_mfma_f32_16x16x32_bf16 v[24:27], v[152:155], v[202:205], v[24:27]
	v_mfma_f32_16x16x32_bf16 v[80:83], v[148:151], v[164:167], v[80:83]
	v_mfma_f32_16x16x32_bf16 v[16:19], v[156:159], v[164:167], v[16:19]
	v_mfma_f32_16x16x32_bf16 v[60:63], v[148:151], v[172:175], v[60:63]
	v_mfma_f32_16x16x32_bf16 v[4:7], v[156:159], v[172:175], v[4:7]
	v_mfma_f32_16x16x32_bf16 v[56:59], v[148:151], v[198:201], v[56:59]
	v_mfma_f32_16x16x32_bf16 v[0:3], v[156:159], v[198:201], v[0:3]
	v_mfma_f32_16x16x32_bf16 v[76:79], v[148:151], v[206:209], v[76:79]
	v_mfma_f32_16x16x32_bf16 v[24:27], v[156:159], v[206:209], v[24:27]
	s_setprio 0
	s_barrier
	s_add_i32 s43, s43, 2
	s_add_u32 s41, s41, 0x10000
	s_addc_u32 s42, s42, 0
	s_add_u32 s8, s8, 0x100
	s_addc_u32 s9, s9, 0
	s_cmp_gt_u32 s43, 13
	s_cbranch_scc0 .LBB0_1278
	s_and_b64 vcc, exec, s[28:29]
	s_cbranch_vccz .LBB0_1281
	s_barrier
.LBB0_1281:
	v_mov_b32_e32 v116, v220
	s_mov_b32 s35, s65
	s_mov_b32 s31, s50
	s_lshl_b32 s16, s31, 8
	v_bfe_u32 v120, v116, 4, 2
	s_lshl_b32 s11, s35, 6
	v_and_b32_e32 v198, 15, v116
	s_add_i32 s11, s11, s16
	v_lshlrev_b32_e32 v199, 4, v120
	v_or3_b32 v122, s11, v198, v199
	s_lshl_b32 s10, s40, 7
	v_cmp_gt_i32_e64 s[8:9], s68, v122
	v_mov_b32_e32 v116, 0
	v_mov_b32_e32 v117, 0
	v_mov_b32_e32 v118, 0
	v_mov_b32_e32 v119, 0
	s_and_saveexec_b64 s[12:13], s[8:9]
	s_cbranch_execz .LBB0_1283
	s_ashr_i32 s11, s11, 6
	s_mul_i32 s42, s11, 0x1600
	s_ashr_i32 s43, s42, 31
	s_lshl_b64 s[42:43], s[42:43], 2
	s_add_u32 s17, s59, s42
	v_bfe_u32 v116, v122, 5, 1
	s_addc_u32 s41, s60, s43
	s_cmp_lt_i32 s11, 3
	v_mul_u32_u24_e32 v116, 0xb00, v116
	s_cselect_b32 s43, s41, s62
	s_cselect_b32 s42, s17, s61
	v_lshlrev_b32_e32 v184, 2, v116
	v_lshl_add_u64 v[116:117], s[42:43], 0, v[184:185]
	s_ashr_i32 s11, s10, 31
	v_lshlrev_b32_e32 v118, 4, v122
	v_lshl_add_u64 v[116:117], s[10:11], 2, v[116:117]
	v_and_b32_e32 v184, 0x1f0, v118
	v_lshl_add_u64 v[116:117], v[116:117], 0, v[184:185]
	v_mov_b32_e32 v116, v248
	v_mov_b32_e32 v117, v249
	v_mov_b32_e32 v118, v250
	v_mov_b32_e32 v119, v251

; #define LAS __attribute__((address_space(3)))
;     __device__ __forceinline__ void operator()(AccT& acc, const pg8::Unit& u, int wr, int wc, int fr, int fq) const {
;     ...
;         asm volatile("s_waitcnt lgkmcnt(0)" ::: "memory"); __builtin_amdgcn_s_barrier(); asm volatile("" ::: "memory");
;         bf16_t* abase = ACT + (size_t)(u.pm * (FF / 64) + 2 * u.pn + (wc >> 1)) * 16384 + (8 * wr + (wc & 1)) * 512 + (((fr * 64 + 16 * fq) ^ ((fr >> 3) << 5)) >> 1);
; #pragma unroll
;         for (int n = 0; n < 2; ++n) {
;             asm volatile("" ::: "memory");
;             f32x4 w0[2], w1[2], w2[2], bb[2];
; #pragma unroll
;             for (int bj = 0; bj < 2; ++bj) { const LAS float* wp = wt + bj * 128 + cl + 4 * n;
;                 w0[bj] = *(const LAS f32x4*)(wp); w1[bj] = *(const LAS f32x4*)(wp + 256); w2[bj] = *(const LAS f32x4*)(wp + 512); bb[bj] = *(const LAS f32x4*)(wp + 768); }
; #pragma unroll
;             for (int ai = 0; ai < 2; ++ai) {
;                 const int blk = 2 * ai + wr;
;                 f32x4 e1[2], e2[2];
; #pragma unroll
;                 for (int bj = 0; bj < 2; ++bj) {
;                     f32x4 v62 = (f32x4){0.f, 0.f, 0.f, 0.f}, v63 = v62;
;                     if (blk > 0) { v62 = *(const LAS f32x4*)(tl + (((blk - 1) * 2 + 0) * 256 + 128 * bj + cl + 4 * n)); v63 = *(const LAS f32x4*)(tl + (((blk - 1) * 2 + 1) * 256 + 128 * bj + cl + 4 * n)); }
.LBB0_1290:
	s_or_b64 exec, exec, s[10:11]
	s_waitcnt lgkmcnt(0)
	s_barrier
	v_add_u32_e32 v96, 0, v201
	v_add_u32_e32 v195, 0x26000, v96
	ds_read_b128 v[104:107], v195
	ds_read_b128 v[96:99], v195 offset:512
	ds_read_b128 v[108:111], v195 offset:1024
	ds_read_b128 v[100:103], v195 offset:1536
	ds_read_b128 v[132:135], v195 offset:2048
	ds_read_b128 v[116:119], v195 offset:2560
	ds_read_b128 v[136:139], v195 offset:3072
	ds_read_b128 v[120:123], v195 offset:3584
	s_cmp_gt_i32 s31, 0
	s_cselect_b64 s[8:9], -1, 0
	s_lshl_b32 s10, s31, 11
	s_add_i32 s91, s10, 0
	s_add_i32 s10, s91, 0x1f800
	s_add_i32 s11, s91, 0x1fc00
	s_cmp_lt_i32 s31, 1
	v_add_u32_e32 v184, s10, v201
	v_add_u32_e32 v202, s11, v201
	v_mov_b32_e32 v160, 0
	v_mov_b32_e32 v164, 0
	v_mov_b32_e32 v165, 0
	v_mov_b32_e32 v166, 0
	v_mov_b32_e32 v167, 0
	v_mov_b32_e32 v168, 0
	v_mov_b32_e32 v169, 0
	v_mov_b32_e32 v170, 0
	v_mov_b32_e32 v171, 0
	s_cbranch_scc1 .LBB0_1292
	ds_read_b128 v[164:167], v184
	ds_read_b128 v[168:171], v202
